# peel the first K-loop trip of every GEMM unit (first MFMA per accumulator takes C=0) and drop the per-unit 128-register zeroing block
# speedup vs baseline: 1.0137x; 1.0029x over previous
; template <class Epi, class Sched, bool ALIGN_EPI = false, bool SP2 = false>
; __device__ __forceinline__ void gemm_phase(PG8_LAS unsigned char* lds, const Gemm g, const Sched& S, const Epi& E) {
;     ...
;         const bool has_next = S.next(ui + 1, nxt);
;         const char* nA = has_next ? (const char*)g.A + (size_t)nxt.pm * tstepA : cA; const char* nB = has_next ? (const char*)g.Bt + (size_t)nxt.pn * tstep : cB;
;         for (int t = 0; t < nt; t += 2) {
;     ...
; #pragma unroll
;         for (int a = 0; a < (Epi::SPLIT ? 1 : 2); ++a)
; #pragma unroll
;             for (int b = 0; b < 2; ++b)
; #pragma unroll
;                 for (int m = 0; m < 4; ++m)
; #pragma unroll
;                     for (int n = 0; n < 2; ++n) acc[a][b][m][n] = (f32x4){0.f, 0.f, 0.f, 0.f};
.LBB0_250:
	s_andn2_b64 vcc, exec, s[16:17]
	s_cbranch_vccnz .Lzt_0
	s_ashr_i32 s23, s22, 31
	s_lshl_b64 s[28:29], s[22:23], 14
	s_add_u32 s24, s24, 0x80
	s_addc_u32 s25, s25, 0
	v_lshl_add_u64 v[216:217], v[210:211], 0, s[28:29]
	s_mov_b64 s[28:29], 0x2000
	s_add_u32 s23, s26, 0x100
	v_lshl_add_u64 v[218:219], v[216:217], 0, s[28:29]
	s_addc_u32 s33, s27, 0
	s_mov_b32 s51, 0

; #define PG8_STAGE(bufoff, gbase, voff) do { _Pragma("unroll") for (int _i = 0; _i < 2; ++_i) \
;         __builtin_amdgcn_global_load_lds((const unsigned*)((const char*)(gbase) + (voff)[_i]), (PG8_LAS unsigned*)(lds + (bufoff) + ldsw + _i * 8192), 16, 0, 0); } while (0)
; #define PG8_LDA(dst, b, h) do { _Pragma("unroll") for (int m = 0; m < 4; ++m) _Pragma("unroll") for (int k = 0; k < 2; ++k) dst[m][k] = *(const PG8_LAS bf16x8*)(lds + PG8_SA(b, h) + aoff + m * 2048 + k * 1024); } while (0)
; #define PG8_MMA(ai, bj, At, Bt) do { __builtin_amdgcn_s_setprio(1); _Pragma("unroll") for (int m = 0; m < 4; ++m) _Pragma("unroll") for (int n = 0; n < 2; ++n) _Pragma("unroll") for (int k = 0; k < 2; ++k) \
;         acc[ai][bj][m][n] = __builtin_amdgcn_mfma_f32_16x16x32_bf16(Bt[n][k], At[m][k], acc[ai][bj][m][n], 0, 0, 0); __builtin_amdgcn_s_setprio(0); } while (0)
; #define PG8_WAIT_V(n) asm volatile("s_waitcnt vmcnt(" #n ")" ::: "memory")
; #define PG8_WAIT_SEL(d, w4, w8) do { if constexpr (Epi::SPLIT) { if (d) { if constexpr (Epi::NSH == 4) PG8_WAIT_V(w4); else PG8_WAIT_V(w8); } else PG8_WAIT_V(8); } else PG8_WAIT_V(8); } while (0)
; #define PG8_WAIT_L(n) asm volatile("s_waitcnt lgkmcnt(" #n ")" ::: "memory")
; #define PG8_BAR __builtin_amdgcn_s_barrier()
; #define PG8_SCHED __builtin_amdgcn_sched_barrier(0)
; template <class Epi, class Sched, bool ALIGN_EPI = false, bool SP2 = false>
; __device__ __forceinline__ void gemm_phase(PG8_LAS unsigned char* lds, const Gemm g, const Sched& S, const Epi& E) {
;     ...
;             PG8_WAIT_L(0); PG8_BAR; PG8_MMA(0, 0, At, B0); PG8_MMA(0, 1, At, B1);
;             if constexpr (Epi::SPLIT) { if (defer) {
;                 E.second(acc, prev, rv1, wr, wc, fr, fq);
;                 _Pragma("unroll") for (int b = 0; b < 2; ++b) _Pragma("unroll") for (int m = 0; m < 4; ++m) _Pragma("unroll") for (int n = 0; n < 2; ++n) acc[1][b][m][n] = (f32x4){0.f, 0.f, 0.f, 0.f}; } }
;             PG8_BAR; PG8_SCHED;
;             PG8_LDA(At, 0, 1); PG8_STAGE(PG8_SB(0, 0), b2, voffB); PG8_STAGE(PG8_SB(0, 1), b2 + hstep, voffB); PG8_STAGE(PG8_SA(0, 0), a2, voffA);
;             if (plast) PG8_WAIT_V(10); else PG8_WAIT_SEL(defer, 16, 24);
.Lpk_ip_259:
	s_add_u32 s30, s24, 0x80
	s_addc_u32 s31, s25, 0
	s_waitcnt lgkmcnt(0)
	s_and_b64 s[26:27], s[26:27], exec
	s_cselect_b32 s27, s7, s31
	s_cselect_b32 s26, s6, s30
	s_cselect_b32 s31, s21, s33
	s_cselect_b32 s30, s20, s23
	s_barrier
	s_setprio 1
	s_waitcnt lgkmcnt(0)
	v_mfma_f32_16x16x32_bf16 v[124:127], v[144:147], v[184:187], 0
	v_mfma_f32_16x16x32_bf16 v[120:123], v[152:155], v[184:187], 0
	v_mfma_f32_16x16x32_bf16 v[108:111], v[144:147], v[176:179], 0
	v_mfma_f32_16x16x32_bf16 v[104:107], v[152:155], v[176:179], 0
	v_mfma_f32_16x16x32_bf16 v[92:95], v[144:147], v[168:171], 0
	v_mfma_f32_16x16x32_bf16 v[88:91], v[152:155], v[168:171], 0
	v_mfma_f32_16x16x32_bf16 v[76:79], v[144:147], v[160:163], 0
	v_mfma_f32_16x16x32_bf16 v[72:75], v[152:155], v[160:163], 0
	v_mfma_f32_16x16x32_bf16 v[124:127], v[148:151], v[188:191], v[124:127]
	v_mfma_f32_16x16x32_bf16 v[120:123], v[156:159], v[188:191], v[120:123]
	v_mfma_f32_16x16x32_bf16 v[108:111], v[148:151], v[180:183], v[108:111]
	v_mfma_f32_16x16x32_bf16 v[104:107], v[156:159], v[180:183], v[104:107]
	v_mfma_f32_16x16x32_bf16 v[92:95], v[148:151], v[172:175], v[92:95]
	v_mfma_f32_16x16x32_bf16 v[88:91], v[156:159], v[172:175], v[88:91]
	v_mfma_f32_16x16x32_bf16 v[76:79], v[148:151], v[164:167], v[76:79]
	v_mfma_f32_16x16x32_bf16 v[72:75], v[156:159], v[164:167], v[72:75]
	s_setprio 0
	s_setprio 1
	v_mfma_f32_16x16x32_bf16 v[116:119], v[128:131], v[184:187], 0
	v_mfma_f32_16x16x32_bf16 v[112:115], v[136:139], v[184:187], 0
	v_mfma_f32_16x16x32_bf16 v[100:103], v[128:131], v[176:179], 0
	v_mfma_f32_16x16x32_bf16 v[96:99], v[136:139], v[176:179], 0
	v_mfma_f32_16x16x32_bf16 v[84:87], v[128:131], v[168:171], 0
	v_mfma_f32_16x16x32_bf16 v[80:83], v[136:139], v[168:171], 0
	v_mfma_f32_16x16x32_bf16 v[68:71], v[128:131], v[160:163], 0
	v_mfma_f32_16x16x32_bf16 v[64:67], v[136:139], v[160:163], 0
	v_mfma_f32_16x16x32_bf16 v[116:119], v[132:135], v[188:191], v[116:119]
	v_mfma_f32_16x16x32_bf16 v[112:115], v[140:143], v[188:191], v[112:115]
	v_mfma_f32_16x16x32_bf16 v[100:103], v[132:135], v[180:183], v[100:103]
	v_mfma_f32_16x16x32_bf16 v[96:99], v[140:143], v[180:183], v[96:99]
	v_mfma_f32_16x16x32_bf16 v[84:87], v[132:135], v[172:175], v[84:87]
	v_mfma_f32_16x16x32_bf16 v[80:83], v[140:143], v[172:175], v[80:83]
	v_mfma_f32_16x16x32_bf16 v[68:71], v[132:135], v[164:167], v[68:71]
	v_mfma_f32_16x16x32_bf16 v[64:67], v[140:143], v[164:167], v[64:67]
	s_setprio 0
	s_barrier
	s_mov_b32 m0, s36
	v_lshl_add_u64 v[222:223], s[30:31], 0, v[192:193]
	v_lshl_add_u64 v[220:221], s[30:31], 0, v[204:205]
	s_add_u32 s30, s30, s12
	ds_read_b128 v[184:187], v240 offset:16384
	ds_read_b128 v[188:191], v240 offset:17408
	ds_read_b128 v[176:179], v240 offset:18432
	ds_read_b128 v[180:183], v240 offset:19456
	ds_read_b128 v[168:171], v240 offset:20480
	ds_read_b128 v[172:175], v240 offset:21504
	ds_read_b128 v[160:163], v240 offset:22528
	ds_read_b128 v[164:167], v240 offset:23552
	global_load_lds_dwordx4 v[222:223], off
	s_mov_b32 m0, s37
	s_addc_u32 s31, s31, s13
	global_load_lds_dwordx4 v[220:221], off
	v_lshl_add_u64 v[230:231], s[30:31], 0, v[192:193]
	s_mov_b32 m0, s38
	v_lshl_add_u64 v[228:229], s[30:31], 0, v[204:205]
	global_load_lds_dwordx4 v[230:231], off
	s_mov_b32 m0, s39
	v_lshl_add_u64 v[224:225], s[26:27], 0, v[208:209]
	global_load_lds_dwordx4 v[228:229], off
	s_mov_b32 m0, s35
	v_lshl_add_u64 v[226:227], s[26:27], 0, v[206:207]
	global_load_lds_dwordx4 v[224:225], off
	s_mov_b32 m0, s40
	s_mov_b64 s[30:31], -1
	global_load_lds_dwordx4 v[226:227], off
	s_and_b64 vcc, exec, s[28:29]
	s_cbranch_vccz .Lpk_ip_261
	s_waitcnt vmcnt(8)
	s_mov_b64 s[30:31], 0

; #define PG8_STAGE(bufoff, gbase, voff) do { _Pragma("unroll") for (int _i = 0; _i < 2; ++_i) \
;         __builtin_amdgcn_global_load_lds((const unsigned*)((const char*)(gbase) + (voff)[_i]), (PG8_LAS unsigned*)(lds + (bufoff) + ldsw + _i * 8192), 16, 0, 0); } while (0)
; #define PG8_LDA(dst, b, h) do { _Pragma("unroll") for (int m = 0; m < 4; ++m) _Pragma("unroll") for (int k = 0; k < 2; ++k) dst[m][k] = *(const PG8_LAS bf16x8*)(lds + PG8_SA(b, h) + aoff + m * 2048 + k * 1024); } while (0)
; #define PG8_LDB(dst, b, h) do { _Pragma("unroll") for (int n = 0; n < 2; ++n) _Pragma("unroll") for (int k = 0; k < 2; ++k) dst[n][k] = *(const PG8_LAS bf16x8*)(lds + PG8_SB(b, h) + boff + n * 2048 + k * 1024); } while (0)
; #define PG8_MMA(ai, bj, At, Bt) do { __builtin_amdgcn_s_setprio(1); _Pragma("unroll") for (int m = 0; m < 4; ++m) _Pragma("unroll") for (int n = 0; n < 2; ++n) _Pragma("unroll") for (int k = 0; k < 2; ++k) \
;         acc[ai][bj][m][n] = __builtin_amdgcn_mfma_f32_16x16x32_bf16(Bt[n][k], At[m][k], acc[ai][bj][m][n], 0, 0, 0); __builtin_amdgcn_s_setprio(0); } while (0)
; #define PG8_WAIT_SEL(d, w4, w8) do { if constexpr (Epi::SPLIT) { if (d) { if constexpr (Epi::NSH == 4) PG8_WAIT_V(w4); else PG8_WAIT_V(w8); } else PG8_WAIT_V(8); } else PG8_WAIT_V(8); } while (0)
; #define PG8_WAIT_L(n) asm volatile("s_waitcnt lgkmcnt(" #n ")" ::: "memory")
; #define PG8_BAR __builtin_amdgcn_s_barrier()
; #define PG8_SCHED __builtin_amdgcn_sched_barrier(0)
; template <class Epi, class Sched, bool ALIGN_EPI = false, bool SP2 = false>
; __device__ __forceinline__ void gemm_phase(PG8_LAS unsigned char* lds, const Gemm g, const Sched& S, const Epi& E) {
;     ...
;             PG8_WAIT_L(0); PG8_BAR; PG8_MMA(1, 0, At, B0); PG8_MMA(1, 1, At, B1); PG8_BAR; PG8_SCHED;
;             PG8_LDB(B0, 1, 0); PG8_LDB(B1, 1, 1); PG8_SCHED; PG8_LDA(At, 1, 0); PG8_STAGE(PG8_SA(0, 1), a2 + hstepA, voffA);
;             PG8_WAIT_SEL(defer, 12, 16); PG8_WAIT_L(0); PG8_BAR; PG8_MMA(0, 0, At, B0); PG8_MMA(0, 1, At, B1); PG8_BAR; PG8_SCHED;
.Lpk_ip_252:
	s_waitcnt lgkmcnt(0)
	s_add_i32 s51, s51, 2
	s_barrier
	s_setprio 1
	s_waitcnt lgkmcnt(0)
	v_mfma_f32_16x16x32_bf16 v[60:63], v[144:147], v[184:187], 0
	v_mfma_f32_16x16x32_bf16 v[56:59], v[152:155], v[184:187], 0
	v_mfma_f32_16x16x32_bf16 v[44:47], v[144:147], v[176:179], 0
	v_mfma_f32_16x16x32_bf16 v[40:43], v[152:155], v[176:179], 0
	v_mfma_f32_16x16x32_bf16 v[28:31], v[144:147], v[168:171], 0
	v_mfma_f32_16x16x32_bf16 v[24:27], v[152:155], v[168:171], 0
	v_mfma_f32_16x16x32_bf16 v[12:15], v[144:147], v[160:163], 0
	v_mfma_f32_16x16x32_bf16 v[8:11], v[152:155], v[160:163], 0
	v_mfma_f32_16x16x32_bf16 v[60:63], v[148:151], v[188:191], v[60:63]
	v_mfma_f32_16x16x32_bf16 v[56:59], v[156:159], v[188:191], v[56:59]
	v_mfma_f32_16x16x32_bf16 v[44:47], v[148:151], v[180:183], v[44:47]
	v_mfma_f32_16x16x32_bf16 v[40:43], v[156:159], v[180:183], v[40:43]
	v_mfma_f32_16x16x32_bf16 v[28:31], v[148:151], v[172:175], v[28:31]
	v_mfma_f32_16x16x32_bf16 v[24:27], v[156:159], v[172:175], v[24:27]
	v_mfma_f32_16x16x32_bf16 v[12:15], v[148:151], v[164:167], v[12:15]
	v_mfma_f32_16x16x32_bf16 v[8:11], v[156:159], v[164:167], v[8:11]
	s_setprio 0
	s_setprio 1
	v_mfma_f32_16x16x32_bf16 v[52:55], v[128:131], v[184:187], 0
	v_mfma_f32_16x16x32_bf16 v[48:51], v[136:139], v[184:187], 0
	v_mfma_f32_16x16x32_bf16 v[36:39], v[128:131], v[176:179], 0
	v_mfma_f32_16x16x32_bf16 v[32:35], v[136:139], v[176:179], 0
	v_mfma_f32_16x16x32_bf16 v[20:23], v[128:131], v[168:171], 0
	v_mfma_f32_16x16x32_bf16 v[16:19], v[136:139], v[168:171], 0
	v_mfma_f32_16x16x32_bf16 v[4:7], v[128:131], v[160:163], 0
	v_mfma_f32_16x16x32_bf16 v[0:3], v[136:139], v[160:163], 0
	v_mfma_f32_16x16x32_bf16 v[52:55], v[132:135], v[188:191], v[52:55]
	v_mfma_f32_16x16x32_bf16 v[48:51], v[140:143], v[188:191], v[48:51]
	v_mfma_f32_16x16x32_bf16 v[36:39], v[132:135], v[180:183], v[36:39]
	v_mfma_f32_16x16x32_bf16 v[32:35], v[140:143], v[180:183], v[32:35]
	v_mfma_f32_16x16x32_bf16 v[20:23], v[132:135], v[172:175], v[20:23]
	v_mfma_f32_16x16x32_bf16 v[16:19], v[140:143], v[172:175], v[16:19]
	v_mfma_f32_16x16x32_bf16 v[4:7], v[132:135], v[164:167], v[4:7]
	v_mfma_f32_16x16x32_bf16 v[0:3], v[140:143], v[164:167], v[0:3]
	s_setprio 0
	s_barrier
	s_add_i32 s28, 0, 0x18000
	s_add_i32 s29, 0, 0x1c000
	v_add_u32_e32 v140, s28, v239
	v_add_u32_e32 v156, s29, v239
	ds_read_b128 v[128:131], v140
	ds_read_b128 v[132:135], v140 offset:1024
	ds_read_b128 v[136:139], v140 offset:2048
	ds_read_b128 v[140:143], v140 offset:3072
	ds_read_b128 v[144:147], v156
	ds_read_b128 v[148:151], v156 offset:1024
	ds_read_b128 v[152:155], v156 offset:2048
	ds_read_b128 v[156:159], v156 offset:3072
	s_add_u32 s26, s26, s8
	s_addc_u32 s27, s27, s9
	s_mov_b32 m0, s41
	v_lshl_add_u64 v[242:243], s[26:27], 0, v[208:209]
	ds_read_b128 v[160:163], v240 offset:32768
	ds_read_b128 v[164:167], v240 offset:33792
	ds_read_b128 v[168:171], v240 offset:34816
	ds_read_b128 v[172:175], v240 offset:35840
	ds_read_b128 v[176:179], v240 offset:36864
	ds_read_b128 v[180:183], v240 offset:37888
	ds_read_b128 v[184:187], v240 offset:38912
	ds_read_b128 v[188:191], v240 offset:39936
	global_load_lds_dwordx4 v[242:243], off
	v_lshl_add_u64 v[242:243], s[26:27], 0, v[206:207]
	s_mov_b32 m0, s42
	s_nop 0
	global_load_lds_dwordx4 v[242:243], off
	s_waitcnt vmcnt(8)
	s_waitcnt lgkmcnt(0)
	s_barrier
	s_setprio 1
	s_waitcnt lgkmcnt(0)
	v_mfma_f32_16x16x32_bf16 v[124:127], v[128:131], v[160:163], v[124:127]
	v_mfma_f32_16x16x32_bf16 v[120:123], v[136:139], v[160:163], v[120:123]
	v_mfma_f32_16x16x32_bf16 v[108:111], v[128:131], v[168:171], v[108:111]
	v_mfma_f32_16x16x32_bf16 v[104:107], v[136:139], v[168:171], v[104:107]
	v_mfma_f32_16x16x32_bf16 v[92:95], v[128:131], v[176:179], v[92:95]
	v_mfma_f32_16x16x32_bf16 v[88:91], v[136:139], v[176:179], v[88:91]
	v_mfma_f32_16x16x32_bf16 v[76:79], v[128:131], v[184:187], v[76:79]
	v_mfma_f32_16x16x32_bf16 v[72:75], v[136:139], v[184:187], v[72:75]
	v_mfma_f32_16x16x32_bf16 v[124:127], v[132:135], v[164:167], v[124:127]
	v_mfma_f32_16x16x32_bf16 v[120:123], v[140:143], v[164:167], v[120:123]
	v_mfma_f32_16x16x32_bf16 v[108:111], v[132:135], v[172:175], v[108:111]
	v_mfma_f32_16x16x32_bf16 v[104:107], v[140:143], v[172:175], v[104:107]
	v_mfma_f32_16x16x32_bf16 v[92:95], v[132:135], v[180:183], v[92:95]
	v_mfma_f32_16x16x32_bf16 v[88:91], v[140:143], v[180:183], v[88:91]
	v_mfma_f32_16x16x32_bf16 v[76:79], v[132:135], v[188:191], v[76:79]
	v_mfma_f32_16x16x32_bf16 v[72:75], v[140:143], v[188:191], v[72:75]
	s_setprio 0
	s_setprio 1
	v_mfma_f32_16x16x32_bf16 v[116:119], v[144:147], v[160:163], v[116:119]
	v_mfma_f32_16x16x32_bf16 v[112:115], v[152:155], v[160:163], v[112:115]
	v_mfma_f32_16x16x32_bf16 v[100:103], v[144:147], v[168:171], v[100:103]
	v_mfma_f32_16x16x32_bf16 v[96:99], v[152:155], v[168:171], v[96:99]
	v_mfma_f32_16x16x32_bf16 v[84:87], v[144:147], v[176:179], v[84:87]
	v_mfma_f32_16x16x32_bf16 v[80:83], v[152:155], v[176:179], v[80:83]
	v_mfma_f32_16x16x32_bf16 v[68:71], v[144:147], v[184:187], v[68:71]
	v_mfma_f32_16x16x32_bf16 v[64:67], v[152:155], v[184:187], v[64:67]
	v_mfma_f32_16x16x32_bf16 v[116:119], v[148:151], v[164:167], v[116:119]
	v_mfma_f32_16x16x32_bf16 v[112:115], v[156:159], v[164:167], v[112:115]
	v_mfma_f32_16x16x32_bf16 v[100:103], v[148:151], v[172:175], v[100:103]
	v_mfma_f32_16x16x32_bf16 v[96:99], v[156:159], v[172:175], v[96:99]
	v_mfma_f32_16x16x32_bf16 v[84:87], v[148:151], v[180:183], v[84:87]
	v_mfma_f32_16x16x32_bf16 v[80:83], v[156:159], v[180:183], v[80:83]
	v_mfma_f32_16x16x32_bf16 v[68:71], v[148:151], v[188:191], v[68:71]
	v_mfma_f32_16x16x32_bf16 v[64:67], v[156:159], v[188:191], v[64:67]
	s_setprio 0
	s_barrier
; #define PG8_STAGE(bufoff, gbase, voff) do { _Pragma("unroll") for (int _i = 0; _i < 2; ++_i) \
;         __builtin_amdgcn_global_load_lds((const unsigned*)((const char*)(gbase) + (voff)[_i]), (PG8_LAS unsigned*)(lds + (bufoff) + ldsw + _i * 8192), 16, 0, 0); } while (0)
; #define PG8_LDA(dst, b, h) do { _Pragma("unroll") for (int m = 0; m < 4; ++m) _Pragma("unroll") for (int k = 0; k < 2; ++k) dst[m][k] = *(const PG8_LAS bf16x8*)(lds + PG8_SA(b, h) + aoff + m * 2048 + k * 1024); } while (0)
; #define PG8_MMA(ai, bj, At, Bt) do { __builtin_amdgcn_s_setprio(1); _Pragma("unroll") for (int m = 0; m < 4; ++m) _Pragma("unroll") for (int n = 0; n < 2; ++n) _Pragma("unroll") for (int k = 0; k < 2; ++k) \
;         acc[ai][bj][m][n] = __builtin_amdgcn_mfma_f32_16x16x32_bf16(Bt[n][k], At[m][k], acc[ai][bj][m][n], 0, 0, 0); __builtin_amdgcn_s_setprio(0); } while (0)
; #define PG8_WAIT_V(n) asm volatile("s_waitcnt vmcnt(" #n ")" ::: "memory")
; #define PG8_WAIT_L(n) asm volatile("s_waitcnt lgkmcnt(" #n ")" ::: "memory")
; #define PG8_BAR __builtin_amdgcn_s_barrier()
; #define PG8_SCHED __builtin_amdgcn_sched_barrier(0)
; template <class Epi, class Sched, bool ALIGN_EPI = false, bool SP2 = false>
; __device__ __forceinline__ void gemm_phase(PG8_LAS unsigned char* lds, const Gemm g, const Sched& S, const Epi& E) {
;     ...
;         for (int t = 0; t < nt; t += 2) {
;     ...
;             PG8_LDA(At, 1, 1); PG8_STAGE(PG8_SB(1, 0), b3, voffB); PG8_STAGE(PG8_SB(1, 1), b3 + hstep, voffB); PG8_STAGE(PG8_SA(1, 0), a3, voffA);
;             PG8_WAIT_V(8); PG8_WAIT_L(0); PG8_BAR; PG8_MMA(1, 0, At, B0); PG8_MMA(1, 1, At, B1); PG8_BAR; PG8_SCHED;
	s_add_i32 s26, s28, s34
	v_lshl_add_u64 v[222:223], v[222:223], 0, s[90:91]
	s_mov_b32 m0, s26
	ds_read_b128 v[160:163], v240 offset:49152
	ds_read_b128 v[164:167], v240 offset:50176
	ds_read_b128 v[168:171], v240 offset:51200
	ds_read_b128 v[172:175], v240 offset:52224
	ds_read_b128 v[176:179], v240 offset:53248
	ds_read_b128 v[180:183], v240 offset:54272
	ds_read_b128 v[184:187], v240 offset:55296
	ds_read_b128 v[188:191], v240 offset:56320
	global_load_lds_dwordx4 v[222:223], off
	v_lshl_add_u64 v[220:221], v[220:221], 0, s[90:91]
	s_add_i32 m0, s26, 0x2000
	s_add_i32 s26, s29, s34
	global_load_lds_dwordx4 v[220:221], off
	v_lshl_add_u64 v[220:221], v[230:231], 0, s[90:91]
	s_mov_b32 m0, s26
	s_nop 0
	global_load_lds_dwordx4 v[220:221], off
	v_lshl_add_u64 v[220:221], v[228:229], 0, s[90:91]
	s_add_i32 m0, s26, 0x2000
	s_nop 0
	global_load_lds_dwordx4 v[220:221], off
	v_lshl_add_u64 v[220:221], v[224:225], 0, s[90:91]
	s_mov_b32 m0, s43
	s_nop 0
	global_load_lds_dwordx4 v[220:221], off
	v_lshl_add_u64 v[220:221], v[226:227], 0, s[90:91]
	s_mov_b32 m0, s44
	s_nop 0
	global_load_lds_dwordx4 v[220:221], off
	s_waitcnt vmcnt(8)
	s_waitcnt lgkmcnt(0)
	s_barrier
	s_setprio 1
	s_waitcnt lgkmcnt(0)
	v_mfma_f32_16x16x32_bf16 v[60:63], v[128:131], v[160:163], v[60:63]
	v_mfma_f32_16x16x32_bf16 v[56:59], v[136:139], v[160:163], v[56:59]
	v_mfma_f32_16x16x32_bf16 v[44:47], v[128:131], v[168:171], v[44:47]
	v_mfma_f32_16x16x32_bf16 v[40:43], v[136:139], v[168:171], v[40:43]
	v_mfma_f32_16x16x32_bf16 v[28:31], v[128:131], v[176:179], v[28:31]
	v_mfma_f32_16x16x32_bf16 v[24:27], v[136:139], v[176:179], v[24:27]
	v_mfma_f32_16x16x32_bf16 v[12:15], v[128:131], v[184:187], v[12:15]
	v_mfma_f32_16x16x32_bf16 v[8:11], v[136:139], v[184:187], v[8:11]
	v_mfma_f32_16x16x32_bf16 v[60:63], v[132:135], v[164:167], v[60:63]
	v_mfma_f32_16x16x32_bf16 v[56:59], v[140:143], v[164:167], v[56:59]
	v_mfma_f32_16x16x32_bf16 v[44:47], v[132:135], v[172:175], v[44:47]
	v_mfma_f32_16x16x32_bf16 v[40:43], v[140:143], v[172:175], v[40:43]
	v_mfma_f32_16x16x32_bf16 v[28:31], v[132:135], v[180:183], v[28:31]
	v_mfma_f32_16x16x32_bf16 v[24:27], v[140:143], v[180:183], v[24:27]
	v_mfma_f32_16x16x32_bf16 v[12:15], v[132:135], v[188:191], v[12:15]
	v_mfma_f32_16x16x32_bf16 v[8:11], v[140:143], v[188:191], v[8:11]
	s_setprio 0
	s_setprio 1
	v_mfma_f32_16x16x32_bf16 v[52:55], v[144:147], v[160:163], v[52:55]
	v_mfma_f32_16x16x32_bf16 v[48:51], v[152:155], v[160:163], v[48:51]
	v_mfma_f32_16x16x32_bf16 v[36:39], v[144:147], v[168:171], v[36:39]
	v_mfma_f32_16x16x32_bf16 v[32:35], v[152:155], v[168:171], v[32:35]
	v_mfma_f32_16x16x32_bf16 v[20:23], v[144:147], v[176:179], v[20:23]
	v_mfma_f32_16x16x32_bf16 v[16:19], v[152:155], v[176:179], v[16:19]
	v_mfma_f32_16x16x32_bf16 v[4:7], v[144:147], v[184:187], v[4:7]
	v_mfma_f32_16x16x32_bf16 v[0:3], v[152:155], v[184:187], v[0:3]
	v_mfma_f32_16x16x32_bf16 v[52:55], v[148:151], v[164:167], v[52:55]
	v_mfma_f32_16x16x32_bf16 v[48:51], v[156:159], v[164:167], v[48:51]
	v_mfma_f32_16x16x32_bf16 v[36:39], v[148:151], v[172:175], v[36:39]
	v_mfma_f32_16x16x32_bf16 v[32:35], v[156:159], v[172:175], v[32:35]
	v_mfma_f32_16x16x32_bf16 v[20:23], v[148:151], v[180:183], v[20:23]
	v_mfma_f32_16x16x32_bf16 v[16:19], v[156:159], v[180:183], v[16:19]
	v_mfma_f32_16x16x32_bf16 v[4:7], v[148:151], v[188:191], v[4:7]
	v_mfma_f32_16x16x32_bf16 v[0:3], v[156:159], v[188:191], v[0:3]
	s_setprio 0
	s_barrier
	s_add_u32 s24, s24, 0x100
	s_addc_u32 s25, s25, 0
	s_add_u32 s23, s23, 0x100
	s_addc_u32 s33, s33, 0
	s_cmp_ge_i32 s51, s45
	s_cbranch_scc1 .LBB0_263
	s_branch .LBB0_253

; #define PG8_STAGE(bufoff, gbase, voff) do { _Pragma("unroll") for (int _i = 0; _i < 2; ++_i) \
;         __builtin_amdgcn_global_load_lds((const unsigned*)((const char*)(gbase) + (voff)[_i]), (PG8_LAS unsigned*)(lds + (bufoff) + ldsw + _i * 8192), 16, 0, 0); } while (0)
; #define PG8_LDA(dst, b, h) do { _Pragma("unroll") for (int m = 0; m < 4; ++m) _Pragma("unroll") for (int k = 0; k < 2; ++k) dst[m][k] = *(const PG8_LAS bf16x8*)(lds + PG8_SA(b, h) + aoff + m * 2048 + k * 1024); } while (0)
; #define PG8_LDB(dst, b, h) do { _Pragma("unroll") for (int n = 0; n < 2; ++n) _Pragma("unroll") for (int k = 0; k < 2; ++k) dst[n][k] = *(const PG8_LAS bf16x8*)(lds + PG8_SB(b, h) + boff + n * 2048 + k * 1024); } while (0)
; #define PG8_MMA(ai, bj, At, Bt) do { __builtin_amdgcn_s_setprio(1); _Pragma("unroll") for (int m = 0; m < 4; ++m) _Pragma("unroll") for (int n = 0; n < 2; ++n) _Pragma("unroll") for (int k = 0; k < 2; ++k) \
;         acc[ai][bj][m][n] = __builtin_amdgcn_mfma_f32_16x16x32_bf16(Bt[n][k], At[m][k], acc[ai][bj][m][n], 0, 0, 0); __builtin_amdgcn_s_setprio(0); } while (0)
; #define PG8_WAIT_V(n) asm volatile("s_waitcnt vmcnt(" #n ")" ::: "memory")
; #define PG8_WAIT_L(n) asm volatile("s_waitcnt lgkmcnt(" #n ")" ::: "memory")
; #define PG8_BAR __builtin_amdgcn_s_barrier()
; template <class Epi, class Sched, bool ALIGN_EPI = false, bool SP2 = false>
; __device__ __forceinline__ void gemm_phase(PG8_LAS unsigned char* lds, const Gemm g, const Sched& S, const Epi& E) {
;     ...
;             PG8_LDB(B0, 0, 0); PG8_LDB(B1, 0, 1); PG8_SCHED; PG8_LDA(At, 0, 0); PG8_STAGE(PG8_SA(1, 1), a1 + hstepA, voffA);
;             if (plast) PG8_WAIT_V(10); else PG8_WAIT_SEL(defer, 12, 16);
;             PG8_WAIT_L(0); PG8_BAR; PG8_MMA(0, 0, At, B0); PG8_MMA(0, 1, At, B1);
;             if constexpr (Epi::SPLIT) { if (defer) {
;                 E.second(acc, prev, rv1, wr, wc, fr, fq);
;                 _Pragma("unroll") for (int b = 0; b < 2; ++b) _Pragma("unroll") for (int m = 0; m < 4; ++m) _Pragma("unroll") for (int n = 0; n < 2; ++n) acc[1][b][m][n] = (f32x4){0.f, 0.f, 0.f, 0.f}; } }
;             PG8_BAR; PG8_SCHED;
;             PG8_LDA(At, 0, 1); PG8_STAGE(PG8_SB(0, 0), b2, voffB); PG8_STAGE(PG8_SB(0, 1), b2 + hstep, voffB); PG8_STAGE(PG8_SA(0, 0), a2, voffA);
;             if (plast) PG8_WAIT_V(10); else PG8_WAIT_SEL(defer, 16, 24);
.LBB0_351:
	s_andn2_b64 vcc, exec, s[22:23]
	s_cbranch_vccnz .Lzt_1
	s_add_u32 s0, s0, 0x80
	s_addc_u32 s1, s1, 0
	s_add_u32 s33, s28, 0x100
	s_addc_u32 s50, s29, 0
	s_mov_b32 s28, 0
.Lpk_op_353:
	s_add_i32 s51, s28, 2
	s_add_u32 s52, s0, 0x80
	s_addc_u32 s29, s1, 0
	s_add_i32 s54, 0, 0x10000
	s_cmp_eq_u32 s45, s28
	s_cselect_b32 s29, s9, s29
	s_cselect_b32 s28, s8, s52
	s_cselect_b32 s53, s27, s50
	s_cselect_b32 s52, s26, s33
	s_add_i32 s55, 0, 0x14000
	v_add_u32_e32 v140, s54, v186
	v_add_u32_e32 v166, s55, v186
	ds_read_b128 v[128:131], v140
	ds_read_b128 v[132:135], v140 offset:1024
	ds_read_b128 v[136:139], v140 offset:2048
	ds_read_b128 v[140:143], v140 offset:3072
	ds_read_b128 v[144:147], v166
	ds_read_b128 v[148:151], v166 offset:1024
	ds_read_b128 v[152:155], v166 offset:2048
	ds_read_b128 v[166:169], v166 offset:3072
	v_lshl_add_u64 v[182:183], s[0:1], 0, v[162:163]
	s_add_i32 m0, s35, 0xc000
	ds_read_b128 v[170:173], v187
	ds_read_b128 v[174:177], v187 offset:1024
	ds_read_b128 v[178:181], v187 offset:2048
	ds_read_b128 v[188:191], v187 offset:3072
	ds_read_b128 v[204:207], v187 offset:4096
	ds_read_b128 v[208:211], v187 offset:5120
	ds_read_b128 v[212:215], v187 offset:6144
	ds_read_b128 v[216:219], v187 offset:7168
	global_load_lds_dwordx4 v[182:183], off
	v_lshl_add_u64 v[182:183], s[0:1], 0, v[164:165]
	s_add_i32 m0, s35, 0xe000
	s_nop 0
	global_load_lds_dwordx4 v[182:183], off
	s_waitcnt vmcnt(8)
	s_waitcnt lgkmcnt(0)
	s_barrier
	s_setprio 1
	s_waitcnt lgkmcnt(0)
	v_mfma_f32_16x16x32_bf16 v[120:123], v[128:131], v[170:173], 0
	v_mfma_f32_16x16x32_bf16 v[124:127], v[136:139], v[170:173], 0
	v_mfma_f32_16x16x32_bf16 v[108:111], v[128:131], v[178:181], 0
	v_mfma_f32_16x16x32_bf16 v[104:107], v[136:139], v[178:181], 0
	v_mfma_f32_16x16x32_bf16 v[92:95], v[128:131], v[204:207], 0
	v_mfma_f32_16x16x32_bf16 v[88:91], v[136:139], v[204:207], 0
	v_mfma_f32_16x16x32_bf16 v[76:79], v[128:131], v[212:215], 0
	v_mfma_f32_16x16x32_bf16 v[72:75], v[136:139], v[212:215], 0
	v_mfma_f32_16x16x32_bf16 v[120:123], v[132:135], v[174:177], v[120:123]
	v_mfma_f32_16x16x32_bf16 v[124:127], v[140:143], v[174:177], v[124:127]
	v_mfma_f32_16x16x32_bf16 v[108:111], v[132:135], v[188:191], v[108:111]
	v_mfma_f32_16x16x32_bf16 v[104:107], v[140:143], v[188:191], v[104:107]
	v_mfma_f32_16x16x32_bf16 v[92:95], v[132:135], v[208:211], v[92:95]
	v_mfma_f32_16x16x32_bf16 v[88:91], v[140:143], v[208:211], v[88:91]
	v_mfma_f32_16x16x32_bf16 v[76:79], v[132:135], v[216:219], v[76:79]
	v_mfma_f32_16x16x32_bf16 v[72:75], v[140:143], v[216:219], v[72:75]
	s_setprio 0
	s_setprio 1
	v_mfma_f32_16x16x32_bf16 v[116:119], v[144:147], v[170:173], 0
	v_mfma_f32_16x16x32_bf16 v[112:115], v[152:155], v[170:173], 0
	v_mfma_f32_16x16x32_bf16 v[100:103], v[144:147], v[178:181], 0
	v_mfma_f32_16x16x32_bf16 v[96:99], v[152:155], v[178:181], 0
	v_mfma_f32_16x16x32_bf16 v[84:87], v[144:147], v[204:207], 0
	v_mfma_f32_16x16x32_bf16 v[80:83], v[152:155], v[204:207], 0
	v_mfma_f32_16x16x32_bf16 v[68:71], v[144:147], v[212:215], 0
	v_mfma_f32_16x16x32_bf16 v[64:67], v[152:155], v[212:215], 0
	v_mfma_f32_16x16x32_bf16 v[116:119], v[148:151], v[174:177], v[116:119]
	v_mfma_f32_16x16x32_bf16 v[112:115], v[166:169], v[174:177], v[112:115]
	v_mfma_f32_16x16x32_bf16 v[100:103], v[148:151], v[188:191], v[100:103]
	v_mfma_f32_16x16x32_bf16 v[96:99], v[166:169], v[188:191], v[96:99]
	v_mfma_f32_16x16x32_bf16 v[84:87], v[148:151], v[208:211], v[84:87]
	v_mfma_f32_16x16x32_bf16 v[80:83], v[166:169], v[208:211], v[80:83]
	v_mfma_f32_16x16x32_bf16 v[68:71], v[148:151], v[216:219], v[68:71]
	v_mfma_f32_16x16x32_bf16 v[64:67], v[166:169], v[216:219], v[64:67]
	s_setprio 0
	s_barrier
	s_add_i32 s54, s54, s34
	v_lshl_add_u64 v[182:183], s[52:53], 0, v[192:193]
	s_mov_b32 m0, s54
	ds_read_b128 v[170:173], v187 offset:16384
	ds_read_b128 v[174:177], v187 offset:17408
	ds_read_b128 v[178:181], v187 offset:18432
	ds_read_b128 v[188:191], v187 offset:19456
	ds_read_b128 v[204:207], v187 offset:20480
	ds_read_b128 v[208:211], v187 offset:21504
	ds_read_b128 v[212:215], v187 offset:22528
	ds_read_b128 v[216:219], v187 offset:23552
	global_load_lds_dwordx4 v[182:183], off
	s_add_i32 m0, s54, 0x2000
	v_lshl_add_u64 v[194:195], s[52:53], 0, v[156:157]
	s_add_u32 s52, s52, s16
	s_addc_u32 s53, s53, s17
	s_add_i32 s54, s55, s34
	global_load_lds_dwordx4 v[194:195], off
	v_lshl_add_u64 v[200:201], s[52:53], 0, v[192:193]
	s_mov_b32 m0, s54
	v_lshl_add_u64 v[202:203], s[52:53], 0, v[156:157]
	global_load_lds_dwordx4 v[200:201], off
	s_add_i32 m0, s54, 0x2000
	v_lshl_add_u64 v[220:221], s[28:29], 0, v[160:161]
	global_load_lds_dwordx4 v[202:203], off
	s_mov_b32 m0, s35
	v_lshl_add_u64 v[222:223], s[28:29], 0, v[158:159]
	global_load_lds_dwordx4 v[220:221], off
	s_mov_b32 m0, s36
	s_nop 0
	global_load_lds_dwordx4 v[222:223], off
	s_waitcnt vmcnt(8)
	s_waitcnt lgkmcnt(0)
	s_barrier
; #define PG8_STAGE(bufoff, gbase, voff) do { _Pragma("unroll") for (int _i = 0; _i < 2; ++_i) \
;         __builtin_amdgcn_global_load_lds((const unsigned*)((const char*)(gbase) + (voff)[_i]), (PG8_LAS unsigned*)(lds + (bufoff) + ldsw + _i * 8192), 16, 0, 0); } while (0)
; #define PG8_LDA(dst, b, h) do { _Pragma("unroll") for (int m = 0; m < 4; ++m) _Pragma("unroll") for (int k = 0; k < 2; ++k) dst[m][k] = *(const PG8_LAS bf16x8*)(lds + PG8_SA(b, h) + aoff + m * 2048 + k * 1024); } while (0)
; #define PG8_LDB(dst, b, h) do { _Pragma("unroll") for (int n = 0; n < 2; ++n) _Pragma("unroll") for (int k = 0; k < 2; ++k) dst[n][k] = *(const PG8_LAS bf16x8*)(lds + PG8_SB(b, h) + boff + n * 2048 + k * 1024); } while (0)
; #define PG8_MMA(ai, bj, At, Bt) do { __builtin_amdgcn_s_setprio(1); _Pragma("unroll") for (int m = 0; m < 4; ++m) _Pragma("unroll") for (int n = 0; n < 2; ++n) _Pragma("unroll") for (int k = 0; k < 2; ++k) \
;         acc[ai][bj][m][n] = __builtin_amdgcn_mfma_f32_16x16x32_bf16(Bt[n][k], At[m][k], acc[ai][bj][m][n], 0, 0, 0); __builtin_amdgcn_s_setprio(0); } while (0)
; #define PG8_WAIT_SEL(d, w4, w8) do { if constexpr (Epi::SPLIT) { if (d) { if constexpr (Epi::NSH == 4) PG8_WAIT_V(w4); else PG8_WAIT_V(w8); } else PG8_WAIT_V(8); } else PG8_WAIT_V(8); } while (0)
; #define PG8_WAIT_L(n) asm volatile("s_waitcnt lgkmcnt(" #n ")" ::: "memory")
; #define PG8_BAR __builtin_amdgcn_s_barrier()
; #define PG8_SCHED __builtin_amdgcn_sched_barrier(0)
; template <class Epi, class Sched, bool ALIGN_EPI = false, bool SP2 = false>
; __device__ __forceinline__ void gemm_phase(PG8_LAS unsigned char* lds, const Gemm g, const Sched& S, const Epi& E) {
;     ...
;             PG8_WAIT_L(0); PG8_BAR; PG8_MMA(1, 0, At, B0); PG8_MMA(1, 1, At, B1); PG8_BAR; PG8_SCHED;
;             PG8_LDB(B0, 1, 0); PG8_LDB(B1, 1, 1); PG8_SCHED; PG8_LDA(At, 1, 0); PG8_STAGE(PG8_SA(0, 1), a2 + hstepA, voffA);
;             PG8_WAIT_SEL(defer, 12, 16); PG8_WAIT_L(0); PG8_BAR; PG8_MMA(0, 0, At, B0); PG8_MMA(0, 1, At, B1); PG8_BAR; PG8_SCHED;
	s_setprio 1
	s_waitcnt lgkmcnt(0)
	v_mfma_f32_16x16x32_bf16 v[60:63], v[128:131], v[170:173], 0
	v_mfma_f32_16x16x32_bf16 v[56:59], v[136:139], v[170:173], 0
	v_mfma_f32_16x16x32_bf16 v[44:47], v[128:131], v[178:181], 0
	v_mfma_f32_16x16x32_bf16 v[40:43], v[136:139], v[178:181], 0
	v_mfma_f32_16x16x32_bf16 v[28:31], v[128:131], v[204:207], 0
	v_mfma_f32_16x16x32_bf16 v[24:27], v[136:139], v[204:207], 0
	v_mfma_f32_16x16x32_bf16 v[12:15], v[128:131], v[212:215], 0
	v_mfma_f32_16x16x32_bf16 v[8:11], v[136:139], v[212:215], 0
	v_mfma_f32_16x16x32_bf16 v[60:63], v[132:135], v[174:177], v[60:63]
	v_mfma_f32_16x16x32_bf16 v[56:59], v[140:143], v[174:177], v[56:59]
	v_mfma_f32_16x16x32_bf16 v[44:47], v[132:135], v[188:191], v[44:47]
	v_mfma_f32_16x16x32_bf16 v[40:43], v[140:143], v[188:191], v[40:43]
	v_mfma_f32_16x16x32_bf16 v[28:31], v[132:135], v[208:211], v[28:31]
	v_mfma_f32_16x16x32_bf16 v[24:27], v[140:143], v[208:211], v[24:27]
	v_mfma_f32_16x16x32_bf16 v[12:15], v[132:135], v[216:219], v[12:15]
	v_mfma_f32_16x16x32_bf16 v[8:11], v[140:143], v[216:219], v[8:11]
	s_setprio 0
	s_setprio 1
	v_mfma_f32_16x16x32_bf16 v[52:55], v[144:147], v[170:173], 0
	v_mfma_f32_16x16x32_bf16 v[48:51], v[152:155], v[170:173], 0
	v_mfma_f32_16x16x32_bf16 v[36:39], v[144:147], v[178:181], 0
	v_mfma_f32_16x16x32_bf16 v[32:35], v[152:155], v[178:181], 0
	v_mfma_f32_16x16x32_bf16 v[20:23], v[144:147], v[204:207], 0
	v_mfma_f32_16x16x32_bf16 v[16:19], v[152:155], v[204:207], 0
	v_mfma_f32_16x16x32_bf16 v[4:7], v[144:147], v[212:215], 0
	v_mfma_f32_16x16x32_bf16 v[0:3], v[152:155], v[212:215], 0
	v_mfma_f32_16x16x32_bf16 v[52:55], v[148:151], v[174:177], v[52:55]
	v_mfma_f32_16x16x32_bf16 v[48:51], v[166:169], v[174:177], v[48:51]
	v_mfma_f32_16x16x32_bf16 v[36:39], v[148:151], v[188:191], v[36:39]
	v_mfma_f32_16x16x32_bf16 v[32:35], v[166:169], v[188:191], v[32:35]
	v_mfma_f32_16x16x32_bf16 v[20:23], v[148:151], v[208:211], v[20:23]
	v_mfma_f32_16x16x32_bf16 v[16:19], v[166:169], v[208:211], v[16:19]
	v_mfma_f32_16x16x32_bf16 v[4:7], v[148:151], v[216:219], v[4:7]
	v_mfma_f32_16x16x32_bf16 v[0:3], v[166:169], v[216:219], v[0:3]
	s_setprio 0
	s_barrier
	s_add_i32 s52, 0, 0x18000
	s_add_i32 s53, 0, 0x1c000
	v_add_u32_e32 v140, s52, v186
	v_add_u32_e32 v166, s53, v186
	ds_read_b128 v[128:131], v140
	ds_read_b128 v[132:135], v140 offset:1024
	ds_read_b128 v[136:139], v140 offset:2048
	ds_read_b128 v[140:143], v140 offset:3072
	ds_read_b128 v[144:147], v166
	ds_read_b128 v[148:151], v166 offset:1024
	ds_read_b128 v[152:155], v166 offset:2048
	ds_read_b128 v[166:169], v166 offset:3072
	s_add_u32 s28, s28, s12
	s_addc_u32 s29, s29, s13
	s_mov_b32 m0, s37
	v_lshl_add_u64 v[224:225], s[28:29], 0, v[160:161]
	ds_read_b128 v[170:173], v187 offset:32768
	ds_read_b128 v[174:177], v187 offset:33792
	ds_read_b128 v[178:181], v187 offset:34816
	ds_read_b128 v[188:191], v187 offset:35840
	ds_read_b128 v[204:207], v187 offset:36864
	ds_read_b128 v[208:211], v187 offset:37888
	ds_read_b128 v[212:215], v187 offset:38912
	ds_read_b128 v[216:219], v187 offset:39936
	global_load_lds_dwordx4 v[224:225], off
	v_lshl_add_u64 v[224:225], s[28:29], 0, v[158:159]
	s_mov_b32 m0, s38
	s_nop 0
	global_load_lds_dwordx4 v[224:225], off
	s_waitcnt vmcnt(8)
	s_waitcnt lgkmcnt(0)
	s_barrier
	s_setprio 1
	s_waitcnt lgkmcnt(0)
	v_mfma_f32_16x16x32_bf16 v[120:123], v[128:131], v[170:173], v[120:123]
	v_mfma_f32_16x16x32_bf16 v[124:127], v[136:139], v[170:173], v[124:127]
	v_mfma_f32_16x16x32_bf16 v[108:111], v[128:131], v[178:181], v[108:111]
	v_mfma_f32_16x16x32_bf16 v[104:107], v[136:139], v[178:181], v[104:107]
	v_mfma_f32_16x16x32_bf16 v[92:95], v[128:131], v[204:207], v[92:95]
	v_mfma_f32_16x16x32_bf16 v[88:91], v[136:139], v[204:207], v[88:91]
	v_mfma_f32_16x16x32_bf16 v[76:79], v[128:131], v[212:215], v[76:79]
	v_mfma_f32_16x16x32_bf16 v[72:75], v[136:139], v[212:215], v[72:75]
	v_mfma_f32_16x16x32_bf16 v[120:123], v[132:135], v[174:177], v[120:123]
	v_mfma_f32_16x16x32_bf16 v[124:127], v[140:143], v[174:177], v[124:127]
	v_mfma_f32_16x16x32_bf16 v[108:111], v[132:135], v[188:191], v[108:111]
	v_mfma_f32_16x16x32_bf16 v[104:107], v[140:143], v[188:191], v[104:107]
	v_mfma_f32_16x16x32_bf16 v[92:95], v[132:135], v[208:211], v[92:95]
	v_mfma_f32_16x16x32_bf16 v[88:91], v[140:143], v[208:211], v[88:91]
	v_mfma_f32_16x16x32_bf16 v[76:79], v[132:135], v[216:219], v[76:79]
	v_mfma_f32_16x16x32_bf16 v[72:75], v[140:143], v[216:219], v[72:75]
	s_setprio 0
	s_setprio 1
	v_mfma_f32_16x16x32_bf16 v[116:119], v[144:147], v[170:173], v[116:119]
	v_mfma_f32_16x16x32_bf16 v[112:115], v[152:155], v[170:173], v[112:115]
	v_mfma_f32_16x16x32_bf16 v[100:103], v[144:147], v[178:181], v[100:103]
	v_mfma_f32_16x16x32_bf16 v[96:99], v[152:155], v[178:181], v[96:99]
	v_mfma_f32_16x16x32_bf16 v[84:87], v[144:147], v[204:207], v[84:87]
	v_mfma_f32_16x16x32_bf16 v[80:83], v[152:155], v[204:207], v[80:83]
	v_mfma_f32_16x16x32_bf16 v[68:71], v[144:147], v[212:215], v[68:71]
	v_mfma_f32_16x16x32_bf16 v[64:67], v[152:155], v[212:215], v[64:67]
	v_mfma_f32_16x16x32_bf16 v[116:119], v[148:151], v[174:177], v[116:119]
	v_mfma_f32_16x16x32_bf16 v[112:115], v[166:169], v[174:177], v[112:115]
	v_mfma_f32_16x16x32_bf16 v[100:103], v[148:151], v[188:191], v[100:103]
	v_mfma_f32_16x16x32_bf16 v[96:99], v[166:169], v[188:191], v[96:99]
	v_mfma_f32_16x16x32_bf16 v[84:87], v[148:151], v[208:211], v[84:87]
	v_mfma_f32_16x16x32_bf16 v[80:83], v[166:169], v[208:211], v[80:83]
	v_mfma_f32_16x16x32_bf16 v[68:71], v[148:151], v[216:219], v[68:71]
	v_mfma_f32_16x16x32_bf16 v[64:67], v[166:169], v[216:219], v[64:67]
	s_setprio 0
	s_barrier
; #define PG8_STAGE(bufoff, gbase, voff) do { _Pragma("unroll") for (int _i = 0; _i < 2; ++_i) \
;         __builtin_amdgcn_global_load_lds((const unsigned*)((const char*)(gbase) + (voff)[_i]), (PG8_LAS unsigned*)(lds + (bufoff) + ldsw + _i * 8192), 16, 0, 0); } while (0)
; #define PG8_LDA(dst, b, h) do { _Pragma("unroll") for (int m = 0; m < 4; ++m) _Pragma("unroll") for (int k = 0; k < 2; ++k) dst[m][k] = *(const PG8_LAS bf16x8*)(lds + PG8_SA(b, h) + aoff + m * 2048 + k * 1024); } while (0)
; #define PG8_MMA(ai, bj, At, Bt) do { __builtin_amdgcn_s_setprio(1); _Pragma("unroll") for (int m = 0; m < 4; ++m) _Pragma("unroll") for (int n = 0; n < 2; ++n) _Pragma("unroll") for (int k = 0; k < 2; ++k) \
;         acc[ai][bj][m][n] = __builtin_amdgcn_mfma_f32_16x16x32_bf16(Bt[n][k], At[m][k], acc[ai][bj][m][n], 0, 0, 0); __builtin_amdgcn_s_setprio(0); } while (0)
; #define PG8_WAIT_V(n) asm volatile("s_waitcnt vmcnt(" #n ")" ::: "memory")
; #define PG8_WAIT_L(n) asm volatile("s_waitcnt lgkmcnt(" #n ")" ::: "memory")
; #define PG8_BAR __builtin_amdgcn_s_barrier()
; #define PG8_SCHED __builtin_amdgcn_sched_barrier(0)
; template <class Epi, class Sched, bool ALIGN_EPI = false, bool SP2 = false>
; __device__ __forceinline__ void gemm_phase(PG8_LAS unsigned char* lds, const Gemm g, const Sched& S, const Epi& E) {
;     ...
;         for (int t = 0; t < nt; t += 2) {
;     ...
;             PG8_LDA(At, 1, 1); PG8_STAGE(PG8_SB(1, 0), b3, voffB); PG8_STAGE(PG8_SB(1, 1), b3 + hstep, voffB); PG8_STAGE(PG8_SA(1, 0), a3, voffA);
;             PG8_WAIT_V(8); PG8_WAIT_L(0); PG8_BAR; PG8_MMA(1, 0, At, B0); PG8_MMA(1, 1, At, B1); PG8_BAR; PG8_SCHED;
	s_add_i32 s28, s52, s34
	v_lshl_add_u64 v[182:183], v[182:183], 0, s[90:91]
	s_mov_b32 m0, s28
	ds_read_b128 v[170:173], v187 offset:49152
	ds_read_b128 v[174:177], v187 offset:50176
	ds_read_b128 v[178:181], v187 offset:51200
	ds_read_b128 v[188:191], v187 offset:52224
	ds_read_b128 v[204:207], v187 offset:53248
	ds_read_b128 v[208:211], v187 offset:54272
	ds_read_b128 v[212:215], v187 offset:55296
	ds_read_b128 v[216:219], v187 offset:56320
	global_load_lds_dwordx4 v[182:183], off
	v_lshl_add_u64 v[182:183], v[194:195], 0, s[90:91]
	s_add_i32 m0, s28, 0x2000
	s_add_i32 s28, s53, s34
	global_load_lds_dwordx4 v[182:183], off
	v_lshl_add_u64 v[182:183], v[200:201], 0, s[90:91]
	s_mov_b32 m0, s28
	s_nop 0
	global_load_lds_dwordx4 v[182:183], off
	v_lshl_add_u64 v[182:183], v[202:203], 0, s[90:91]
	s_add_i32 m0, s28, 0x2000
	s_nop 0
	global_load_lds_dwordx4 v[182:183], off
	v_lshl_add_u64 v[182:183], v[220:221], 0, s[90:91]
	s_mov_b32 m0, s43
	s_nop 0
	global_load_lds_dwordx4 v[182:183], off
	v_lshl_add_u64 v[182:183], v[222:223], 0, s[90:91]
	s_mov_b32 m0, s44
	s_nop 0
	global_load_lds_dwordx4 v[182:183], off
	s_waitcnt vmcnt(8)
	s_waitcnt lgkmcnt(0)
	s_barrier
	s_setprio 1
	s_waitcnt lgkmcnt(0)
	v_mfma_f32_16x16x32_bf16 v[60:63], v[128:131], v[170:173], v[60:63]
	v_mfma_f32_16x16x32_bf16 v[56:59], v[136:139], v[170:173], v[56:59]
	v_mfma_f32_16x16x32_bf16 v[44:47], v[128:131], v[178:181], v[44:47]
	v_mfma_f32_16x16x32_bf16 v[40:43], v[136:139], v[178:181], v[40:43]
	v_mfma_f32_16x16x32_bf16 v[28:31], v[128:131], v[204:207], v[28:31]
	v_mfma_f32_16x16x32_bf16 v[24:27], v[136:139], v[204:207], v[24:27]
	v_mfma_f32_16x16x32_bf16 v[12:15], v[128:131], v[212:215], v[12:15]
	v_mfma_f32_16x16x32_bf16 v[8:11], v[136:139], v[212:215], v[8:11]
	v_mfma_f32_16x16x32_bf16 v[60:63], v[132:135], v[174:177], v[60:63]
	v_mfma_f32_16x16x32_bf16 v[56:59], v[140:143], v[174:177], v[56:59]
	v_mfma_f32_16x16x32_bf16 v[44:47], v[132:135], v[188:191], v[44:47]
	v_mfma_f32_16x16x32_bf16 v[40:43], v[140:143], v[188:191], v[40:43]
	v_mfma_f32_16x16x32_bf16 v[28:31], v[132:135], v[208:211], v[28:31]
	v_mfma_f32_16x16x32_bf16 v[24:27], v[140:143], v[208:211], v[24:27]
	v_mfma_f32_16x16x32_bf16 v[12:15], v[132:135], v[216:219], v[12:15]
	v_mfma_f32_16x16x32_bf16 v[8:11], v[140:143], v[216:219], v[8:11]
	s_setprio 0
	s_setprio 1
	v_mfma_f32_16x16x32_bf16 v[52:55], v[144:147], v[170:173], v[52:55]
	v_mfma_f32_16x16x32_bf16 v[48:51], v[152:155], v[170:173], v[48:51]
	v_mfma_f32_16x16x32_bf16 v[36:39], v[144:147], v[178:181], v[36:39]
	v_mfma_f32_16x16x32_bf16 v[32:35], v[152:155], v[178:181], v[32:35]
	v_mfma_f32_16x16x32_bf16 v[20:23], v[144:147], v[204:207], v[20:23]
	v_mfma_f32_16x16x32_bf16 v[16:19], v[152:155], v[204:207], v[16:19]
	v_mfma_f32_16x16x32_bf16 v[4:7], v[144:147], v[212:215], v[4:7]
	v_mfma_f32_16x16x32_bf16 v[0:3], v[152:155], v[212:215], v[0:3]
	v_mfma_f32_16x16x32_bf16 v[52:55], v[148:151], v[174:177], v[52:55]
	v_mfma_f32_16x16x32_bf16 v[48:51], v[166:169], v[174:177], v[48:51]
	v_mfma_f32_16x16x32_bf16 v[36:39], v[148:151], v[188:191], v[36:39]
	v_mfma_f32_16x16x32_bf16 v[32:35], v[166:169], v[188:191], v[32:35]
	v_mfma_f32_16x16x32_bf16 v[20:23], v[148:151], v[208:211], v[20:23]
	v_mfma_f32_16x16x32_bf16 v[16:19], v[166:169], v[208:211], v[16:19]
	v_mfma_f32_16x16x32_bf16 v[4:7], v[148:151], v[216:219], v[4:7]
	v_mfma_f32_16x16x32_bf16 v[0:3], v[166:169], v[216:219], v[0:3]
	s_setprio 0
	s_barrier
	s_add_u32 s0, s0, 0x100
	s_addc_u32 s1, s1, 0
	s_add_u32 s33, s33, 0x100
	s_addc_u32 s50, s50, 0
	s_cmp_ge_i32 s51, s40
	s_mov_b32 s28, s51
	s_cbranch_scc0 .LBB0_353
	s_branch .LBB0_354

; template <class Epi, class Sched, bool ALIGN_EPI = false, bool SP2 = false>
; __device__ __forceinline__ void gemm_phase(PG8_LAS unsigned char* lds, const Gemm g, const Sched& S, const Epi& E) {
;     ...
;         const bool has_next = S.next(ui + 1, nxt);
;         const char* nA = has_next ? (const char*)g.A + (size_t)nxt.pm * tstepA : cA; const char* nB = has_next ? (const char*)g.Bt + (size_t)nxt.pn * tstep : cB;
;         for (int t = 0; t < nt; t += 2) {
;     ...
; #pragma unroll
;         for (int a = 0; a < (Epi::SPLIT ? 1 : 2); ++a)
; #pragma unroll
;             for (int b = 0; b < 2; ++b)
; #pragma unroll
;                 for (int m = 0; m < 4; ++m)
; #pragma unroll
;                     for (int n = 0; n < 2; ++n) acc[a][b][m][n] = (f32x4){0.f, 0.f, 0.f, 0.f};
.LBB0_410:
	s_andn2_b64 vcc, exec, s[22:23]
	s_cbranch_vccnz .Lzt_2
	s_ashr_i32 s1, s0, 31
	s_lshl_b64 s[30:31], s[0:1], 14
	s_add_u32 s26, s26, 0x80
	s_addc_u32 s27, s27, 0
	v_lshl_add_u64 v[216:217], v[210:211], 0, s[30:31]
	s_mov_b64 s[30:31], 0x2000
	s_add_u32 s1, s28, 0x100
	v_lshl_add_u64 v[218:219], v[216:217], 0, s[30:31]
	s_addc_u32 s33, s29, 0
	s_mov_b32 s55, 0

; #define PG8_STAGE(bufoff, gbase, voff) do { _Pragma("unroll") for (int _i = 0; _i < 2; ++_i) \
;         __builtin_amdgcn_global_load_lds((const unsigned*)((const char*)(gbase) + (voff)[_i]), (PG8_LAS unsigned*)(lds + (bufoff) + ldsw + _i * 8192), 16, 0, 0); } while (0)
; #define PG8_LDA(dst, b, h) do { _Pragma("unroll") for (int m = 0; m < 4; ++m) _Pragma("unroll") for (int k = 0; k < 2; ++k) dst[m][k] = *(const PG8_LAS bf16x8*)(lds + PG8_SA(b, h) + aoff + m * 2048 + k * 1024); } while (0)
; #define PG8_MMA(ai, bj, At, Bt) do { __builtin_amdgcn_s_setprio(1); _Pragma("unroll") for (int m = 0; m < 4; ++m) _Pragma("unroll") for (int n = 0; n < 2; ++n) _Pragma("unroll") for (int k = 0; k < 2; ++k) \
;         acc[ai][bj][m][n] = __builtin_amdgcn_mfma_f32_16x16x32_bf16(Bt[n][k], At[m][k], acc[ai][bj][m][n], 0, 0, 0); __builtin_amdgcn_s_setprio(0); } while (0)
; #define PG8_WAIT_V(n) asm volatile("s_waitcnt vmcnt(" #n ")" ::: "memory")
; #define PG8_WAIT_SEL(d, w4, w8) do { if constexpr (Epi::SPLIT) { if (d) { if constexpr (Epi::NSH == 4) PG8_WAIT_V(w4); else PG8_WAIT_V(w8); } else PG8_WAIT_V(8); } else PG8_WAIT_V(8); } while (0)
; #define PG8_WAIT_L(n) asm volatile("s_waitcnt lgkmcnt(" #n ")" ::: "memory")
; #define PG8_BAR __builtin_amdgcn_s_barrier()
; #define PG8_SCHED __builtin_amdgcn_sched_barrier(0)
; template <class Epi, class Sched, bool ALIGN_EPI = false, bool SP2 = false>
; __device__ __forceinline__ void gemm_phase(PG8_LAS unsigned char* lds, const Gemm g, const Sched& S, const Epi& E) {
;     ...
;             PG8_WAIT_L(0); PG8_BAR; PG8_MMA(0, 0, At, B0); PG8_MMA(0, 1, At, B1);
;             if constexpr (Epi::SPLIT) { if (defer) {
;                 E.second(acc, prev, rv1, wr, wc, fr, fq);
;                 _Pragma("unroll") for (int b = 0; b < 2; ++b) _Pragma("unroll") for (int m = 0; m < 4; ++m) _Pragma("unroll") for (int n = 0; n < 2; ++n) acc[1][b][m][n] = (f32x4){0.f, 0.f, 0.f, 0.f}; } }
;             PG8_BAR; PG8_SCHED;
;             PG8_LDA(At, 0, 1); PG8_STAGE(PG8_SB(0, 0), b2, voffB); PG8_STAGE(PG8_SB(0, 1), b2 + hstep, voffB); PG8_STAGE(PG8_SA(0, 0), a2, voffA);
;             if (plast) PG8_WAIT_V(10); else PG8_WAIT_SEL(defer, 16, 24);
.Lpk_gu_419:
	s_add_u32 s34, s26, 0x80
	s_addc_u32 s35, s27, 0
	s_waitcnt lgkmcnt(0)
	s_and_b64 s[28:29], s[28:29], exec
	s_cselect_b32 s29, s9, s35
	s_cselect_b32 s28, s8, s34
	s_cselect_b32 s35, s11, s33
	s_cselect_b32 s34, s10, s1
	s_barrier
	s_setprio 1
	s_waitcnt lgkmcnt(0)
	v_mfma_f32_16x16x32_bf16 v[120:123], v[144:147], v[184:187], 0
	v_mfma_f32_16x16x32_bf16 v[112:115], v[152:155], v[184:187], 0
	v_mfma_f32_16x16x32_bf16 v[104:107], v[144:147], v[176:179], 0
	v_mfma_f32_16x16x32_bf16 v[96:99], v[152:155], v[176:179], 0
	v_mfma_f32_16x16x32_bf16 v[88:91], v[144:147], v[168:171], 0
	v_mfma_f32_16x16x32_bf16 v[80:83], v[152:155], v[168:171], 0
	v_mfma_f32_16x16x32_bf16 v[72:75], v[144:147], v[160:163], 0
	v_mfma_f32_16x16x32_bf16 v[64:67], v[152:155], v[160:163], 0
	v_mfma_f32_16x16x32_bf16 v[120:123], v[148:151], v[188:191], v[120:123]
	v_mfma_f32_16x16x32_bf16 v[112:115], v[156:159], v[188:191], v[112:115]
	v_mfma_f32_16x16x32_bf16 v[104:107], v[148:151], v[180:183], v[104:107]
	v_mfma_f32_16x16x32_bf16 v[96:99], v[156:159], v[180:183], v[96:99]
	v_mfma_f32_16x16x32_bf16 v[88:91], v[148:151], v[172:175], v[88:91]
	v_mfma_f32_16x16x32_bf16 v[80:83], v[156:159], v[172:175], v[80:83]
	v_mfma_f32_16x16x32_bf16 v[72:75], v[148:151], v[164:167], v[72:75]
	v_mfma_f32_16x16x32_bf16 v[64:67], v[156:159], v[164:167], v[64:67]
	s_setprio 0
	s_setprio 1
	v_mfma_f32_16x16x32_bf16 v[124:127], v[128:131], v[184:187], 0
	v_mfma_f32_16x16x32_bf16 v[116:119], v[136:139], v[184:187], 0
	v_mfma_f32_16x16x32_bf16 v[108:111], v[128:131], v[176:179], 0
	v_mfma_f32_16x16x32_bf16 v[100:103], v[136:139], v[176:179], 0
	v_mfma_f32_16x16x32_bf16 v[92:95], v[128:131], v[168:171], 0
	v_mfma_f32_16x16x32_bf16 v[84:87], v[136:139], v[168:171], 0
	v_mfma_f32_16x16x32_bf16 v[76:79], v[128:131], v[160:163], 0
	v_mfma_f32_16x16x32_bf16 v[68:71], v[136:139], v[160:163], 0
	v_mfma_f32_16x16x32_bf16 v[124:127], v[132:135], v[188:191], v[124:127]
	v_mfma_f32_16x16x32_bf16 v[116:119], v[140:143], v[188:191], v[116:119]
	v_mfma_f32_16x16x32_bf16 v[108:111], v[132:135], v[180:183], v[108:111]
	v_mfma_f32_16x16x32_bf16 v[100:103], v[140:143], v[180:183], v[100:103]
	v_mfma_f32_16x16x32_bf16 v[92:95], v[132:135], v[172:175], v[92:95]
	v_mfma_f32_16x16x32_bf16 v[84:87], v[140:143], v[172:175], v[84:87]
	v_mfma_f32_16x16x32_bf16 v[76:79], v[132:135], v[164:167], v[76:79]
	v_mfma_f32_16x16x32_bf16 v[68:71], v[140:143], v[164:167], v[68:71]
	s_setprio 0
	s_barrier
	s_mov_b32 m0, s40
	v_lshl_add_u64 v[222:223], s[34:35], 0, v[192:193]
	v_lshl_add_u64 v[220:221], s[34:35], 0, v[204:205]
	s_add_u32 s34, s34, s16
	ds_read_b128 v[184:187], v240 offset:16384
	ds_read_b128 v[188:191], v240 offset:17408
	ds_read_b128 v[176:179], v240 offset:18432
	ds_read_b128 v[180:183], v240 offset:19456
	ds_read_b128 v[168:171], v240 offset:20480
	ds_read_b128 v[172:175], v240 offset:21504
	ds_read_b128 v[160:163], v240 offset:22528
	ds_read_b128 v[164:167], v240 offset:23552
	global_load_lds_dwordx4 v[222:223], off
	s_mov_b32 m0, s41
	s_addc_u32 s35, s35, s17
	global_load_lds_dwordx4 v[220:221], off
	v_lshl_add_u64 v[230:231], s[34:35], 0, v[192:193]
	s_mov_b32 m0, s42
	v_lshl_add_u64 v[228:229], s[34:35], 0, v[204:205]
	global_load_lds_dwordx4 v[230:231], off
	s_mov_b32 m0, s43
	v_lshl_add_u64 v[224:225], s[28:29], 0, v[208:209]
	global_load_lds_dwordx4 v[228:229], off
	s_mov_b32 m0, s39
	v_lshl_add_u64 v[226:227], s[28:29], 0, v[206:207]
	global_load_lds_dwordx4 v[224:225], off
	s_mov_b32 m0, s44
	s_mov_b64 s[34:35], -1
	global_load_lds_dwordx4 v[226:227], off
	s_and_b64 vcc, exec, s[30:31]
	s_cbranch_vccz .Lpk_gu_421
	s_waitcnt vmcnt(8)
	s_mov_b64 s[34:35], 0

; #define PG8_STAGE(bufoff, gbase, voff) do { _Pragma("unroll") for (int _i = 0; _i < 2; ++_i) \
;         __builtin_amdgcn_global_load_lds((const unsigned*)((const char*)(gbase) + (voff)[_i]), (PG8_LAS unsigned*)(lds + (bufoff) + ldsw + _i * 8192), 16, 0, 0); } while (0)
; #define PG8_LDA(dst, b, h) do { _Pragma("unroll") for (int m = 0; m < 4; ++m) _Pragma("unroll") for (int k = 0; k < 2; ++k) dst[m][k] = *(const PG8_LAS bf16x8*)(lds + PG8_SA(b, h) + aoff + m * 2048 + k * 1024); } while (0)
; #define PG8_LDB(dst, b, h) do { _Pragma("unroll") for (int n = 0; n < 2; ++n) _Pragma("unroll") for (int k = 0; k < 2; ++k) dst[n][k] = *(const PG8_LAS bf16x8*)(lds + PG8_SB(b, h) + boff + n * 2048 + k * 1024); } while (0)
; #define PG8_MMA(ai, bj, At, Bt) do { __builtin_amdgcn_s_setprio(1); _Pragma("unroll") for (int m = 0; m < 4; ++m) _Pragma("unroll") for (int n = 0; n < 2; ++n) _Pragma("unroll") for (int k = 0; k < 2; ++k) \
;         acc[ai][bj][m][n] = __builtin_amdgcn_mfma_f32_16x16x32_bf16(Bt[n][k], At[m][k], acc[ai][bj][m][n], 0, 0, 0); __builtin_amdgcn_s_setprio(0); } while (0)
; #define PG8_WAIT_SEL(d, w4, w8) do { if constexpr (Epi::SPLIT) { if (d) { if constexpr (Epi::NSH == 4) PG8_WAIT_V(w4); else PG8_WAIT_V(w8); } else PG8_WAIT_V(8); } else PG8_WAIT_V(8); } while (0)
; #define PG8_WAIT_L(n) asm volatile("s_waitcnt lgkmcnt(" #n ")" ::: "memory")
; #define PG8_BAR __builtin_amdgcn_s_barrier()
; #define PG8_SCHED __builtin_amdgcn_sched_barrier(0)
; template <class Epi, class Sched, bool ALIGN_EPI = false, bool SP2 = false>
; __device__ __forceinline__ void gemm_phase(PG8_LAS unsigned char* lds, const Gemm g, const Sched& S, const Epi& E) {
;     ...
;             PG8_WAIT_L(0); PG8_BAR; PG8_MMA(1, 0, At, B0); PG8_MMA(1, 1, At, B1); PG8_BAR; PG8_SCHED;
;             PG8_LDB(B0, 1, 0); PG8_LDB(B1, 1, 1); PG8_SCHED; PG8_LDA(At, 1, 0); PG8_STAGE(PG8_SA(0, 1), a2 + hstepA, voffA);
;             PG8_WAIT_SEL(defer, 12, 16); PG8_WAIT_L(0); PG8_BAR; PG8_MMA(0, 0, At, B0); PG8_MMA(0, 1, At, B1); PG8_BAR; PG8_SCHED;
.Lpk_gu_412:
	s_waitcnt lgkmcnt(0)
	s_add_i32 s55, s55, 2
	s_barrier
	s_setprio 1
	s_waitcnt lgkmcnt(0)
	v_mfma_f32_16x16x32_bf16 v[56:59], v[144:147], v[184:187], 0
	v_mfma_f32_16x16x32_bf16 v[48:51], v[152:155], v[184:187], 0
	v_mfma_f32_16x16x32_bf16 v[40:43], v[144:147], v[176:179], 0
	v_mfma_f32_16x16x32_bf16 v[32:35], v[152:155], v[176:179], 0
	v_mfma_f32_16x16x32_bf16 v[24:27], v[144:147], v[168:171], 0
	v_mfma_f32_16x16x32_bf16 v[16:19], v[152:155], v[168:171], 0
	v_mfma_f32_16x16x32_bf16 v[8:11], v[144:147], v[160:163], 0
	v_mfma_f32_16x16x32_bf16 v[4:7], v[152:155], v[160:163], 0
	v_mfma_f32_16x16x32_bf16 v[56:59], v[148:151], v[188:191], v[56:59]
	v_mfma_f32_16x16x32_bf16 v[48:51], v[156:159], v[188:191], v[48:51]
	v_mfma_f32_16x16x32_bf16 v[40:43], v[148:151], v[180:183], v[40:43]
	v_mfma_f32_16x16x32_bf16 v[32:35], v[156:159], v[180:183], v[32:35]
	v_mfma_f32_16x16x32_bf16 v[24:27], v[148:151], v[172:175], v[24:27]
	v_mfma_f32_16x16x32_bf16 v[16:19], v[156:159], v[172:175], v[16:19]
	v_mfma_f32_16x16x32_bf16 v[8:11], v[148:151], v[164:167], v[8:11]
	v_mfma_f32_16x16x32_bf16 v[4:7], v[156:159], v[164:167], v[4:7]
	s_setprio 0
	s_setprio 1
	v_mfma_f32_16x16x32_bf16 v[60:63], v[128:131], v[184:187], 0
	v_mfma_f32_16x16x32_bf16 v[52:55], v[136:139], v[184:187], 0
	v_mfma_f32_16x16x32_bf16 v[44:47], v[128:131], v[176:179], 0
	v_mfma_f32_16x16x32_bf16 v[36:39], v[136:139], v[176:179], 0
	v_mfma_f32_16x16x32_bf16 v[28:31], v[128:131], v[168:171], 0
	v_mfma_f32_16x16x32_bf16 v[20:23], v[136:139], v[168:171], 0
	v_mfma_f32_16x16x32_bf16 v[12:15], v[128:131], v[160:163], 0
	v_mfma_f32_16x16x32_bf16 v[0:3], v[136:139], v[160:163], 0
	v_mfma_f32_16x16x32_bf16 v[60:63], v[132:135], v[188:191], v[60:63]
	v_mfma_f32_16x16x32_bf16 v[52:55], v[140:143], v[188:191], v[52:55]
	v_mfma_f32_16x16x32_bf16 v[44:47], v[132:135], v[180:183], v[44:47]
	v_mfma_f32_16x16x32_bf16 v[36:39], v[140:143], v[180:183], v[36:39]
	v_mfma_f32_16x16x32_bf16 v[28:31], v[132:135], v[172:175], v[28:31]
	v_mfma_f32_16x16x32_bf16 v[20:23], v[140:143], v[172:175], v[20:23]
	v_mfma_f32_16x16x32_bf16 v[12:15], v[132:135], v[164:167], v[12:15]
	v_mfma_f32_16x16x32_bf16 v[0:3], v[140:143], v[164:167], v[0:3]
	s_setprio 0
	s_barrier
	s_add_i32 s30, 0, 0x18000
	s_add_i32 s31, 0, 0x1c000
	v_add_u32_e32 v140, s30, v239
	v_add_u32_e32 v156, s31, v239
	ds_read_b128 v[128:131], v140
	ds_read_b128 v[132:135], v140 offset:1024
	ds_read_b128 v[136:139], v140 offset:2048
	ds_read_b128 v[140:143], v140 offset:3072
	ds_read_b128 v[144:147], v156
	ds_read_b128 v[148:151], v156 offset:1024
	ds_read_b128 v[152:155], v156 offset:2048
	ds_read_b128 v[156:159], v156 offset:3072
	s_add_u32 s28, s28, s12
	s_addc_u32 s29, s29, s13
	s_mov_b32 m0, s45
	v_lshl_add_u64 v[194:195], s[28:29], 0, v[208:209]
	ds_read_b128 v[160:163], v240 offset:32768
	ds_read_b128 v[164:167], v240 offset:33792
	ds_read_b128 v[168:171], v240 offset:34816
	ds_read_b128 v[172:175], v240 offset:35840
	ds_read_b128 v[176:179], v240 offset:36864
	ds_read_b128 v[180:183], v240 offset:37888
	ds_read_b128 v[184:187], v240 offset:38912
	ds_read_b128 v[188:191], v240 offset:39936
	global_load_lds_dwordx4 v[194:195], off
	v_lshl_add_u64 v[194:195], s[28:29], 0, v[206:207]
	s_mov_b32 m0, s46
	s_nop 0
	global_load_lds_dwordx4 v[194:195], off
	s_waitcnt vmcnt(8)
	s_waitcnt lgkmcnt(0)
	s_barrier
	s_setprio 1
	s_waitcnt lgkmcnt(0)
	v_mfma_f32_16x16x32_bf16 v[120:123], v[128:131], v[160:163], v[120:123]
	v_mfma_f32_16x16x32_bf16 v[112:115], v[136:139], v[160:163], v[112:115]
	v_mfma_f32_16x16x32_bf16 v[104:107], v[128:131], v[168:171], v[104:107]
	v_mfma_f32_16x16x32_bf16 v[96:99], v[136:139], v[168:171], v[96:99]
	v_mfma_f32_16x16x32_bf16 v[88:91], v[128:131], v[176:179], v[88:91]
	v_mfma_f32_16x16x32_bf16 v[80:83], v[136:139], v[176:179], v[80:83]
	v_mfma_f32_16x16x32_bf16 v[72:75], v[128:131], v[184:187], v[72:75]
	v_mfma_f32_16x16x32_bf16 v[64:67], v[136:139], v[184:187], v[64:67]
	v_mfma_f32_16x16x32_bf16 v[120:123], v[132:135], v[164:167], v[120:123]
	v_mfma_f32_16x16x32_bf16 v[112:115], v[140:143], v[164:167], v[112:115]
	v_mfma_f32_16x16x32_bf16 v[104:107], v[132:135], v[172:175], v[104:107]
	v_mfma_f32_16x16x32_bf16 v[96:99], v[140:143], v[172:175], v[96:99]
	v_mfma_f32_16x16x32_bf16 v[88:91], v[132:135], v[180:183], v[88:91]
	v_mfma_f32_16x16x32_bf16 v[80:83], v[140:143], v[180:183], v[80:83]
	v_mfma_f32_16x16x32_bf16 v[72:75], v[132:135], v[188:191], v[72:75]
	v_mfma_f32_16x16x32_bf16 v[64:67], v[140:143], v[188:191], v[64:67]
	s_setprio 0
	s_setprio 1
	v_mfma_f32_16x16x32_bf16 v[124:127], v[144:147], v[160:163], v[124:127]
	v_mfma_f32_16x16x32_bf16 v[116:119], v[152:155], v[160:163], v[116:119]
	v_mfma_f32_16x16x32_bf16 v[108:111], v[144:147], v[168:171], v[108:111]
	v_mfma_f32_16x16x32_bf16 v[100:103], v[152:155], v[168:171], v[100:103]
	v_mfma_f32_16x16x32_bf16 v[92:95], v[144:147], v[176:179], v[92:95]
	v_mfma_f32_16x16x32_bf16 v[84:87], v[152:155], v[176:179], v[84:87]
	v_mfma_f32_16x16x32_bf16 v[76:79], v[144:147], v[184:187], v[76:79]
	v_mfma_f32_16x16x32_bf16 v[68:71], v[152:155], v[184:187], v[68:71]
	v_mfma_f32_16x16x32_bf16 v[124:127], v[148:151], v[164:167], v[124:127]
	v_mfma_f32_16x16x32_bf16 v[116:119], v[156:159], v[164:167], v[116:119]
	v_mfma_f32_16x16x32_bf16 v[108:111], v[148:151], v[172:175], v[108:111]
	v_mfma_f32_16x16x32_bf16 v[100:103], v[156:159], v[172:175], v[100:103]
	v_mfma_f32_16x16x32_bf16 v[92:95], v[148:151], v[180:183], v[92:95]
	v_mfma_f32_16x16x32_bf16 v[84:87], v[156:159], v[180:183], v[84:87]
	v_mfma_f32_16x16x32_bf16 v[76:79], v[148:151], v[188:191], v[76:79]
	v_mfma_f32_16x16x32_bf16 v[68:71], v[156:159], v[188:191], v[68:71]
	s_setprio 0
	s_barrier
; #define PG8_STAGE(bufoff, gbase, voff) do { _Pragma("unroll") for (int _i = 0; _i < 2; ++_i) \
;         __builtin_amdgcn_global_load_lds((const unsigned*)((const char*)(gbase) + (voff)[_i]), (PG8_LAS unsigned*)(lds + (bufoff) + ldsw + _i * 8192), 16, 0, 0); } while (0)
; #define PG8_LDA(dst, b, h) do { _Pragma("unroll") for (int m = 0; m < 4; ++m) _Pragma("unroll") for (int k = 0; k < 2; ++k) dst[m][k] = *(const PG8_LAS bf16x8*)(lds + PG8_SA(b, h) + aoff + m * 2048 + k * 1024); } while (0)
; #define PG8_MMA(ai, bj, At, Bt) do { __builtin_amdgcn_s_setprio(1); _Pragma("unroll") for (int m = 0; m < 4; ++m) _Pragma("unroll") for (int n = 0; n < 2; ++n) _Pragma("unroll") for (int k = 0; k < 2; ++k) \
;         acc[ai][bj][m][n] = __builtin_amdgcn_mfma_f32_16x16x32_bf16(Bt[n][k], At[m][k], acc[ai][bj][m][n], 0, 0, 0); __builtin_amdgcn_s_setprio(0); } while (0)
; #define PG8_WAIT_V(n) asm volatile("s_waitcnt vmcnt(" #n ")" ::: "memory")
; #define PG8_WAIT_L(n) asm volatile("s_waitcnt lgkmcnt(" #n ")" ::: "memory")
; #define PG8_BAR __builtin_amdgcn_s_barrier()
; #define PG8_SCHED __builtin_amdgcn_sched_barrier(0)
; template <class Epi, class Sched, bool ALIGN_EPI = false, bool SP2 = false>
; __device__ __forceinline__ void gemm_phase(PG8_LAS unsigned char* lds, const Gemm g, const Sched& S, const Epi& E) {
;     ...
;         for (int t = 0; t < nt; t += 2) {
;     ...
;             PG8_LDA(At, 1, 1); PG8_STAGE(PG8_SB(1, 0), b3, voffB); PG8_STAGE(PG8_SB(1, 1), b3 + hstep, voffB); PG8_STAGE(PG8_SA(1, 0), a3, voffA);
;             PG8_WAIT_V(8); PG8_WAIT_L(0); PG8_BAR; PG8_MMA(1, 0, At, B0); PG8_MMA(1, 1, At, B1); PG8_BAR; PG8_SCHED;
	s_add_i32 s28, s30, s38
	v_lshl_add_u64 v[194:195], v[222:223], 0, s[90:91]
	s_mov_b32 m0, s28
	ds_read_b128 v[160:163], v240 offset:49152
	ds_read_b128 v[164:167], v240 offset:50176
	ds_read_b128 v[168:171], v240 offset:51200
	ds_read_b128 v[172:175], v240 offset:52224
	ds_read_b128 v[176:179], v240 offset:53248
	ds_read_b128 v[180:183], v240 offset:54272
	ds_read_b128 v[184:187], v240 offset:55296
	ds_read_b128 v[188:191], v240 offset:56320
	global_load_lds_dwordx4 v[194:195], off
	v_lshl_add_u64 v[194:195], v[220:221], 0, s[90:91]
	s_add_i32 m0, s28, 0x2000
	s_add_i32 s28, s31, s38
	global_load_lds_dwordx4 v[194:195], off
	v_lshl_add_u64 v[194:195], v[230:231], 0, s[90:91]
	s_mov_b32 m0, s28
	s_nop 0
	global_load_lds_dwordx4 v[194:195], off
	v_lshl_add_u64 v[194:195], v[228:229], 0, s[90:91]
	s_add_i32 m0, s28, 0x2000
	s_nop 0
	global_load_lds_dwordx4 v[194:195], off
	v_lshl_add_u64 v[194:195], v[224:225], 0, s[90:91]
	s_mov_b32 m0, s49
	s_nop 0
	global_load_lds_dwordx4 v[194:195], off
	v_lshl_add_u64 v[194:195], v[226:227], 0, s[90:91]
	s_mov_b32 m0, s50
	s_nop 0
	global_load_lds_dwordx4 v[194:195], off
	s_waitcnt vmcnt(8)
	s_waitcnt lgkmcnt(0)
	s_barrier
	s_setprio 1
	s_waitcnt lgkmcnt(0)
	v_mfma_f32_16x16x32_bf16 v[56:59], v[128:131], v[160:163], v[56:59]
	v_mfma_f32_16x16x32_bf16 v[48:51], v[136:139], v[160:163], v[48:51]
	v_mfma_f32_16x16x32_bf16 v[40:43], v[128:131], v[168:171], v[40:43]
	v_mfma_f32_16x16x32_bf16 v[32:35], v[136:139], v[168:171], v[32:35]
	v_mfma_f32_16x16x32_bf16 v[24:27], v[128:131], v[176:179], v[24:27]
	v_mfma_f32_16x16x32_bf16 v[16:19], v[136:139], v[176:179], v[16:19]
	v_mfma_f32_16x16x32_bf16 v[8:11], v[128:131], v[184:187], v[8:11]
	v_mfma_f32_16x16x32_bf16 v[4:7], v[136:139], v[184:187], v[4:7]
	v_mfma_f32_16x16x32_bf16 v[56:59], v[132:135], v[164:167], v[56:59]
	v_mfma_f32_16x16x32_bf16 v[48:51], v[140:143], v[164:167], v[48:51]
	v_mfma_f32_16x16x32_bf16 v[40:43], v[132:135], v[172:175], v[40:43]
	v_mfma_f32_16x16x32_bf16 v[32:35], v[140:143], v[172:175], v[32:35]
	v_mfma_f32_16x16x32_bf16 v[24:27], v[132:135], v[180:183], v[24:27]
	v_mfma_f32_16x16x32_bf16 v[16:19], v[140:143], v[180:183], v[16:19]
	v_mfma_f32_16x16x32_bf16 v[8:11], v[132:135], v[188:191], v[8:11]
	v_mfma_f32_16x16x32_bf16 v[4:7], v[140:143], v[188:191], v[4:7]
	s_setprio 0
	s_setprio 1
	v_mfma_f32_16x16x32_bf16 v[60:63], v[144:147], v[160:163], v[60:63]
	v_mfma_f32_16x16x32_bf16 v[52:55], v[152:155], v[160:163], v[52:55]
	v_mfma_f32_16x16x32_bf16 v[44:47], v[144:147], v[168:171], v[44:47]
	v_mfma_f32_16x16x32_bf16 v[36:39], v[152:155], v[168:171], v[36:39]
	v_mfma_f32_16x16x32_bf16 v[28:31], v[144:147], v[176:179], v[28:31]
	v_mfma_f32_16x16x32_bf16 v[20:23], v[152:155], v[176:179], v[20:23]
	v_mfma_f32_16x16x32_bf16 v[12:15], v[144:147], v[184:187], v[12:15]
	v_mfma_f32_16x16x32_bf16 v[0:3], v[152:155], v[184:187], v[0:3]
	v_mfma_f32_16x16x32_bf16 v[60:63], v[148:151], v[164:167], v[60:63]
	v_mfma_f32_16x16x32_bf16 v[52:55], v[156:159], v[164:167], v[52:55]
	v_mfma_f32_16x16x32_bf16 v[44:47], v[148:151], v[172:175], v[44:47]
	v_mfma_f32_16x16x32_bf16 v[36:39], v[156:159], v[172:175], v[36:39]
	v_mfma_f32_16x16x32_bf16 v[28:31], v[148:151], v[180:183], v[28:31]
	v_mfma_f32_16x16x32_bf16 v[20:23], v[156:159], v[180:183], v[20:23]
	v_mfma_f32_16x16x32_bf16 v[12:15], v[148:151], v[188:191], v[12:15]
	v_mfma_f32_16x16x32_bf16 v[0:3], v[156:159], v[188:191], v[0:3]
	s_setprio 0
	s_barrier
	s_add_u32 s26, s26, 0x100
	s_addc_u32 s27, s27, 0
	s_add_u32 s1, s1, 0x100
	s_addc_u32 s33, s33, 0
	s_cmp_ge_i32 s55, s47
	s_cbranch_scc1 .LBB0_423
	s_branch .LBB0_413

; #define PG8_STAGE(bufoff, gbase, voff) do { _Pragma("unroll") for (int _i = 0; _i < 2; ++_i) \
;         __builtin_amdgcn_global_load_lds((const unsigned*)((const char*)(gbase) + (voff)[_i]), (PG8_LAS unsigned*)(lds + (bufoff) + ldsw + _i * 8192), 16, 0, 0); } while (0)
; #define PG8_LDA(dst, b, h) do { _Pragma("unroll") for (int m = 0; m < 4; ++m) _Pragma("unroll") for (int k = 0; k < 2; ++k) dst[m][k] = *(const PG8_LAS bf16x8*)(lds + PG8_SA(b, h) + aoff + m * 2048 + k * 1024); } while (0)
; #define PG8_LDB(dst, b, h) do { _Pragma("unroll") for (int n = 0; n < 2; ++n) _Pragma("unroll") for (int k = 0; k < 2; ++k) dst[n][k] = *(const PG8_LAS bf16x8*)(lds + PG8_SB(b, h) + boff + n * 2048 + k * 1024); } while (0)
; #define PG8_MMA(ai, bj, At, Bt) do { __builtin_amdgcn_s_setprio(1); _Pragma("unroll") for (int m = 0; m < 4; ++m) _Pragma("unroll") for (int n = 0; n < 2; ++n) _Pragma("unroll") for (int k = 0; k < 2; ++k) \
;         acc[ai][bj][m][n] = __builtin_amdgcn_mfma_f32_16x16x32_bf16(Bt[n][k], At[m][k], acc[ai][bj][m][n], 0, 0, 0); __builtin_amdgcn_s_setprio(0); } while (0)
; #define PG8_WAIT_V(n) asm volatile("s_waitcnt vmcnt(" #n ")" ::: "memory")
; #define PG8_WAIT_L(n) asm volatile("s_waitcnt lgkmcnt(" #n ")" ::: "memory")
; #define PG8_BAR __builtin_amdgcn_s_barrier()
; template <class Epi, class Sched, bool ALIGN_EPI = false, bool SP2 = false>
; __device__ __forceinline__ void gemm_phase(PG8_LAS unsigned char* lds, const Gemm g, const Sched& S, const Epi& E) {
;     ...
;             PG8_LDB(B0, 0, 0); PG8_LDB(B1, 0, 1); PG8_SCHED; PG8_LDA(At, 0, 0); PG8_STAGE(PG8_SA(1, 1), a1 + hstepA, voffA);
;             if (plast) PG8_WAIT_V(10); else PG8_WAIT_SEL(defer, 12, 16);
;             PG8_WAIT_L(0); PG8_BAR; PG8_MMA(0, 0, At, B0); PG8_MMA(0, 1, At, B1);
;             if constexpr (Epi::SPLIT) { if (defer) {
;                 E.second(acc, prev, rv1, wr, wc, fr, fq);
;                 _Pragma("unroll") for (int b = 0; b < 2; ++b) _Pragma("unroll") for (int m = 0; m < 4; ++m) _Pragma("unroll") for (int n = 0; n < 2; ++n) acc[1][b][m][n] = (f32x4){0.f, 0.f, 0.f, 0.f}; } }
;             PG8_BAR; PG8_SCHED;
;             PG8_LDA(At, 0, 1); PG8_STAGE(PG8_SB(0, 0), b2, voffB); PG8_STAGE(PG8_SB(0, 1), b2 + hstep, voffB); PG8_STAGE(PG8_SA(0, 0), a2, voffA);
;             if (plast) PG8_WAIT_V(10); else PG8_WAIT_SEL(defer, 16, 24);
.LBB0_462:
	s_andn2_b64 vcc, exec, s[18:19]
	s_cbranch_vccnz .Lzt_3
	s_add_u32 s24, s24, 0x80
	s_addc_u32 s25, s25, 0
	s_add_u32 s33, s26, 0x100
	s_addc_u32 s48, s27, 0
	s_mov_b32 s26, 0
.Lpk_pp_464:
	s_add_i32 s49, s26, 2
	s_add_u32 s50, s24, 0x80
	s_addc_u32 s27, s25, 0
	s_add_i32 s52, 0, 0x10000
	s_cmp_eq_u32 s42, s26
	s_cselect_b32 s27, s9, s27
	s_cselect_b32 s26, s8, s50
	s_cselect_b32 s51, s23, s48
	s_cselect_b32 s50, s22, s33
	s_add_i32 s53, 0, 0x14000
	v_add_u32_e32 v154, s52, v140
	v_add_u32_e32 v170, s53, v140
	ds_read_b128 v[142:145], v154
	ds_read_b128 v[146:149], v154 offset:1024
	ds_read_b128 v[150:153], v154 offset:2048
	ds_read_b128 v[154:157], v154 offset:3072
	ds_read_b128 v[158:161], v170
	ds_read_b128 v[162:165], v170 offset:1024
	ds_read_b128 v[166:169], v170 offset:2048
	ds_read_b128 v[170:173], v170 offset:3072
	v_lshl_add_u64 v[190:191], s[24:25], 0, v[134:135]
	s_add_i32 m0, s34, 0xc000
	ds_read_b128 v[174:177], v141
	ds_read_b128 v[178:181], v141 offset:1024
	ds_read_b128 v[182:185], v141 offset:2048
	ds_read_b128 v[186:189], v141 offset:3072
	ds_read_b128 v[204:207], v141 offset:4096
	ds_read_b128 v[208:211], v141 offset:5120
	ds_read_b128 v[212:215], v141 offset:6144
	ds_read_b128 v[216:219], v141 offset:7168
	global_load_lds_dwordx4 v[190:191], off
	v_lshl_add_u64 v[190:191], s[24:25], 0, v[136:137]
	s_add_i32 m0, s34, 0xe000
	s_nop 0
	global_load_lds_dwordx4 v[190:191], off
	s_waitcnt vmcnt(8)
	s_waitcnt lgkmcnt(0)
	s_barrier
	s_setprio 1
	s_waitcnt lgkmcnt(0)
	v_mfma_f32_16x16x32_bf16 v[120:123], v[142:145], v[174:177], 0
	v_mfma_f32_16x16x32_bf16 v[124:127], v[150:153], v[174:177], 0
	v_mfma_f32_16x16x32_bf16 v[108:111], v[142:145], v[182:185], 0
	v_mfma_f32_16x16x32_bf16 v[104:107], v[150:153], v[182:185], 0
	v_mfma_f32_16x16x32_bf16 v[92:95], v[142:145], v[204:207], 0
	v_mfma_f32_16x16x32_bf16 v[88:91], v[150:153], v[204:207], 0
	v_mfma_f32_16x16x32_bf16 v[76:79], v[142:145], v[212:215], 0
	v_mfma_f32_16x16x32_bf16 v[72:75], v[150:153], v[212:215], 0
	v_mfma_f32_16x16x32_bf16 v[120:123], v[146:149], v[178:181], v[120:123]
	v_mfma_f32_16x16x32_bf16 v[124:127], v[154:157], v[178:181], v[124:127]
	v_mfma_f32_16x16x32_bf16 v[108:111], v[146:149], v[186:189], v[108:111]
	v_mfma_f32_16x16x32_bf16 v[104:107], v[154:157], v[186:189], v[104:107]
	v_mfma_f32_16x16x32_bf16 v[92:95], v[146:149], v[208:211], v[92:95]
	v_mfma_f32_16x16x32_bf16 v[88:91], v[154:157], v[208:211], v[88:91]
	v_mfma_f32_16x16x32_bf16 v[76:79], v[146:149], v[216:219], v[76:79]
	v_mfma_f32_16x16x32_bf16 v[72:75], v[154:157], v[216:219], v[72:75]
	s_setprio 0
	s_setprio 1
	v_mfma_f32_16x16x32_bf16 v[116:119], v[158:161], v[174:177], 0
	v_mfma_f32_16x16x32_bf16 v[112:115], v[166:169], v[174:177], 0
	v_mfma_f32_16x16x32_bf16 v[100:103], v[158:161], v[182:185], 0
	v_mfma_f32_16x16x32_bf16 v[96:99], v[166:169], v[182:185], 0
	v_mfma_f32_16x16x32_bf16 v[84:87], v[158:161], v[204:207], 0
	v_mfma_f32_16x16x32_bf16 v[80:83], v[166:169], v[204:207], 0
	v_mfma_f32_16x16x32_bf16 v[68:71], v[158:161], v[212:215], 0
	v_mfma_f32_16x16x32_bf16 v[64:67], v[166:169], v[212:215], 0
	v_mfma_f32_16x16x32_bf16 v[116:119], v[162:165], v[178:181], v[116:119]
	v_mfma_f32_16x16x32_bf16 v[112:115], v[170:173], v[178:181], v[112:115]
	v_mfma_f32_16x16x32_bf16 v[100:103], v[162:165], v[186:189], v[100:103]
	v_mfma_f32_16x16x32_bf16 v[96:99], v[170:173], v[186:189], v[96:99]
	v_mfma_f32_16x16x32_bf16 v[84:87], v[162:165], v[208:211], v[84:87]
	v_mfma_f32_16x16x32_bf16 v[80:83], v[170:173], v[208:211], v[80:83]
	v_mfma_f32_16x16x32_bf16 v[68:71], v[162:165], v[216:219], v[68:71]
	v_mfma_f32_16x16x32_bf16 v[64:67], v[170:173], v[216:219], v[64:67]
	s_setprio 0
	s_barrier
	s_add_i32 s52, s52, s31
	v_lshl_add_u64 v[190:191], s[50:51], 0, v[192:193]
	s_mov_b32 m0, s52
	ds_read_b128 v[174:177], v141 offset:16384
	ds_read_b128 v[178:181], v141 offset:17408
	ds_read_b128 v[182:185], v141 offset:18432
	ds_read_b128 v[186:189], v141 offset:19456
	ds_read_b128 v[204:207], v141 offset:20480
	ds_read_b128 v[208:211], v141 offset:21504
	ds_read_b128 v[212:215], v141 offset:22528
	ds_read_b128 v[216:219], v141 offset:23552
	global_load_lds_dwordx4 v[190:191], off
	s_add_i32 m0, s52, 0x2000
	v_lshl_add_u64 v[194:195], s[50:51], 0, v[128:129]
	s_add_u32 s50, s50, s12
	s_addc_u32 s51, s51, s13
	s_add_i32 s52, s53, s31
	global_load_lds_dwordx4 v[194:195], off
	v_lshl_add_u64 v[200:201], s[50:51], 0, v[192:193]
	s_mov_b32 m0, s52
	v_lshl_add_u64 v[202:203], s[50:51], 0, v[128:129]
	global_load_lds_dwordx4 v[200:201], off
	s_add_i32 m0, s52, 0x2000
	v_lshl_add_u64 v[220:221], s[26:27], 0, v[132:133]
	global_load_lds_dwordx4 v[202:203], off
	s_mov_b32 m0, s34
	v_lshl_add_u64 v[222:223], s[26:27], 0, v[130:131]
	global_load_lds_dwordx4 v[220:221], off
	s_mov_b32 m0, s35
	s_nop 0
	global_load_lds_dwordx4 v[222:223], off
	s_waitcnt vmcnt(8)
	s_waitcnt lgkmcnt(0)
	s_barrier
; #define PG8_STAGE(bufoff, gbase, voff) do { _Pragma("unroll") for (int _i = 0; _i < 2; ++_i) \
;         __builtin_amdgcn_global_load_lds((const unsigned*)((const char*)(gbase) + (voff)[_i]), (PG8_LAS unsigned*)(lds + (bufoff) + ldsw + _i * 8192), 16, 0, 0); } while (0)
; #define PG8_LDA(dst, b, h) do { _Pragma("unroll") for (int m = 0; m < 4; ++m) _Pragma("unroll") for (int k = 0; k < 2; ++k) dst[m][k] = *(const PG8_LAS bf16x8*)(lds + PG8_SA(b, h) + aoff + m * 2048 + k * 1024); } while (0)
; #define PG8_LDB(dst, b, h) do { _Pragma("unroll") for (int n = 0; n < 2; ++n) _Pragma("unroll") for (int k = 0; k < 2; ++k) dst[n][k] = *(const PG8_LAS bf16x8*)(lds + PG8_SB(b, h) + boff + n * 2048 + k * 1024); } while (0)
; #define PG8_MMA(ai, bj, At, Bt) do { __builtin_amdgcn_s_setprio(1); _Pragma("unroll") for (int m = 0; m < 4; ++m) _Pragma("unroll") for (int n = 0; n < 2; ++n) _Pragma("unroll") for (int k = 0; k < 2; ++k) \
;         acc[ai][bj][m][n] = __builtin_amdgcn_mfma_f32_16x16x32_bf16(Bt[n][k], At[m][k], acc[ai][bj][m][n], 0, 0, 0); __builtin_amdgcn_s_setprio(0); } while (0)
; #define PG8_WAIT_SEL(d, w4, w8) do { if constexpr (Epi::SPLIT) { if (d) { if constexpr (Epi::NSH == 4) PG8_WAIT_V(w4); else PG8_WAIT_V(w8); } else PG8_WAIT_V(8); } else PG8_WAIT_V(8); } while (0)
; #define PG8_WAIT_L(n) asm volatile("s_waitcnt lgkmcnt(" #n ")" ::: "memory")
; #define PG8_BAR __builtin_amdgcn_s_barrier()
; #define PG8_SCHED __builtin_amdgcn_sched_barrier(0)
; template <class Epi, class Sched, bool ALIGN_EPI = false, bool SP2 = false>
; __device__ __forceinline__ void gemm_phase(PG8_LAS unsigned char* lds, const Gemm g, const Sched& S, const Epi& E) {
;     ...
;             PG8_WAIT_L(0); PG8_BAR; PG8_MMA(1, 0, At, B0); PG8_MMA(1, 1, At, B1); PG8_BAR; PG8_SCHED;
;             PG8_LDB(B0, 1, 0); PG8_LDB(B1, 1, 1); PG8_SCHED; PG8_LDA(At, 1, 0); PG8_STAGE(PG8_SA(0, 1), a2 + hstepA, voffA);
;             PG8_WAIT_SEL(defer, 12, 16); PG8_WAIT_L(0); PG8_BAR; PG8_MMA(0, 0, At, B0); PG8_MMA(0, 1, At, B1); PG8_BAR; PG8_SCHED;
	s_setprio 1
	s_waitcnt lgkmcnt(0)
	v_mfma_f32_16x16x32_bf16 v[60:63], v[142:145], v[174:177], 0
	v_mfma_f32_16x16x32_bf16 v[56:59], v[150:153], v[174:177], 0
	v_mfma_f32_16x16x32_bf16 v[44:47], v[142:145], v[182:185], 0
	v_mfma_f32_16x16x32_bf16 v[40:43], v[150:153], v[182:185], 0
	v_mfma_f32_16x16x32_bf16 v[28:31], v[142:145], v[204:207], 0
	v_mfma_f32_16x16x32_bf16 v[24:27], v[150:153], v[204:207], 0
	v_mfma_f32_16x16x32_bf16 v[12:15], v[142:145], v[212:215], 0
	v_mfma_f32_16x16x32_bf16 v[8:11], v[150:153], v[212:215], 0
	v_mfma_f32_16x16x32_bf16 v[60:63], v[146:149], v[178:181], v[60:63]
	v_mfma_f32_16x16x32_bf16 v[56:59], v[154:157], v[178:181], v[56:59]
	v_mfma_f32_16x16x32_bf16 v[44:47], v[146:149], v[186:189], v[44:47]
	v_mfma_f32_16x16x32_bf16 v[40:43], v[154:157], v[186:189], v[40:43]
	v_mfma_f32_16x16x32_bf16 v[28:31], v[146:149], v[208:211], v[28:31]
	v_mfma_f32_16x16x32_bf16 v[24:27], v[154:157], v[208:211], v[24:27]
	v_mfma_f32_16x16x32_bf16 v[12:15], v[146:149], v[216:219], v[12:15]
	v_mfma_f32_16x16x32_bf16 v[8:11], v[154:157], v[216:219], v[8:11]
	s_setprio 0
	s_setprio 1
	v_mfma_f32_16x16x32_bf16 v[52:55], v[158:161], v[174:177], 0
	v_mfma_f32_16x16x32_bf16 v[48:51], v[166:169], v[174:177], 0
	v_mfma_f32_16x16x32_bf16 v[36:39], v[158:161], v[182:185], 0
	v_mfma_f32_16x16x32_bf16 v[32:35], v[166:169], v[182:185], 0
	v_mfma_f32_16x16x32_bf16 v[20:23], v[158:161], v[204:207], 0
	v_mfma_f32_16x16x32_bf16 v[16:19], v[166:169], v[204:207], 0
	v_mfma_f32_16x16x32_bf16 v[4:7], v[158:161], v[212:215], 0
	v_mfma_f32_16x16x32_bf16 v[0:3], v[166:169], v[212:215], 0
	v_mfma_f32_16x16x32_bf16 v[52:55], v[162:165], v[178:181], v[52:55]
	v_mfma_f32_16x16x32_bf16 v[48:51], v[170:173], v[178:181], v[48:51]
	v_mfma_f32_16x16x32_bf16 v[36:39], v[162:165], v[186:189], v[36:39]
	v_mfma_f32_16x16x32_bf16 v[32:35], v[170:173], v[186:189], v[32:35]
	v_mfma_f32_16x16x32_bf16 v[20:23], v[162:165], v[208:211], v[20:23]
	v_mfma_f32_16x16x32_bf16 v[16:19], v[170:173], v[208:211], v[16:19]
	v_mfma_f32_16x16x32_bf16 v[4:7], v[162:165], v[216:219], v[4:7]
	v_mfma_f32_16x16x32_bf16 v[0:3], v[170:173], v[216:219], v[0:3]
	s_setprio 0
	s_barrier
	s_add_i32 s50, 0, 0x18000
	s_add_i32 s51, 0, 0x1c000
	v_add_u32_e32 v154, s50, v140
	v_add_u32_e32 v170, s51, v140
	ds_read_b128 v[142:145], v154
	ds_read_b128 v[146:149], v154 offset:1024
	ds_read_b128 v[150:153], v154 offset:2048
	ds_read_b128 v[154:157], v154 offset:3072
	ds_read_b128 v[158:161], v170
	ds_read_b128 v[162:165], v170 offset:1024
	ds_read_b128 v[166:169], v170 offset:2048
	ds_read_b128 v[170:173], v170 offset:3072
	s_add_u32 s26, s26, s0
	s_addc_u32 s27, s27, s1
	s_mov_b32 m0, s36
	v_lshl_add_u64 v[224:225], s[26:27], 0, v[132:133]
	ds_read_b128 v[174:177], v141 offset:32768
	ds_read_b128 v[178:181], v141 offset:33792
	ds_read_b128 v[182:185], v141 offset:34816
	ds_read_b128 v[186:189], v141 offset:35840
	ds_read_b128 v[204:207], v141 offset:36864
	ds_read_b128 v[208:211], v141 offset:37888
	ds_read_b128 v[212:215], v141 offset:38912
	ds_read_b128 v[216:219], v141 offset:39936
	global_load_lds_dwordx4 v[224:225], off
	v_lshl_add_u64 v[224:225], s[26:27], 0, v[130:131]
	s_mov_b32 m0, s37
	s_nop 0
	global_load_lds_dwordx4 v[224:225], off
	s_waitcnt vmcnt(8)
	s_waitcnt lgkmcnt(0)
	s_barrier
	s_setprio 1
	s_waitcnt lgkmcnt(0)
	v_mfma_f32_16x16x32_bf16 v[120:123], v[142:145], v[174:177], v[120:123]
	v_mfma_f32_16x16x32_bf16 v[124:127], v[150:153], v[174:177], v[124:127]
	v_mfma_f32_16x16x32_bf16 v[108:111], v[142:145], v[182:185], v[108:111]
	v_mfma_f32_16x16x32_bf16 v[104:107], v[150:153], v[182:185], v[104:107]
	v_mfma_f32_16x16x32_bf16 v[92:95], v[142:145], v[204:207], v[92:95]
	v_mfma_f32_16x16x32_bf16 v[88:91], v[150:153], v[204:207], v[88:91]
	v_mfma_f32_16x16x32_bf16 v[76:79], v[142:145], v[212:215], v[76:79]
	v_mfma_f32_16x16x32_bf16 v[72:75], v[150:153], v[212:215], v[72:75]
	v_mfma_f32_16x16x32_bf16 v[120:123], v[146:149], v[178:181], v[120:123]
	v_mfma_f32_16x16x32_bf16 v[124:127], v[154:157], v[178:181], v[124:127]
	v_mfma_f32_16x16x32_bf16 v[108:111], v[146:149], v[186:189], v[108:111]
	v_mfma_f32_16x16x32_bf16 v[104:107], v[154:157], v[186:189], v[104:107]
	v_mfma_f32_16x16x32_bf16 v[92:95], v[146:149], v[208:211], v[92:95]
	v_mfma_f32_16x16x32_bf16 v[88:91], v[154:157], v[208:211], v[88:91]
	v_mfma_f32_16x16x32_bf16 v[76:79], v[146:149], v[216:219], v[76:79]
	v_mfma_f32_16x16x32_bf16 v[72:75], v[154:157], v[216:219], v[72:75]
	s_setprio 0
	s_setprio 1
	v_mfma_f32_16x16x32_bf16 v[116:119], v[158:161], v[174:177], v[116:119]
	v_mfma_f32_16x16x32_bf16 v[112:115], v[166:169], v[174:177], v[112:115]
	v_mfma_f32_16x16x32_bf16 v[100:103], v[158:161], v[182:185], v[100:103]
	v_mfma_f32_16x16x32_bf16 v[96:99], v[166:169], v[182:185], v[96:99]
	v_mfma_f32_16x16x32_bf16 v[84:87], v[158:161], v[204:207], v[84:87]
	v_mfma_f32_16x16x32_bf16 v[80:83], v[166:169], v[204:207], v[80:83]
	v_mfma_f32_16x16x32_bf16 v[68:71], v[158:161], v[212:215], v[68:71]
	v_mfma_f32_16x16x32_bf16 v[64:67], v[166:169], v[212:215], v[64:67]
	v_mfma_f32_16x16x32_bf16 v[116:119], v[162:165], v[178:181], v[116:119]
	v_mfma_f32_16x16x32_bf16 v[112:115], v[170:173], v[178:181], v[112:115]
	v_mfma_f32_16x16x32_bf16 v[100:103], v[162:165], v[186:189], v[100:103]
	v_mfma_f32_16x16x32_bf16 v[96:99], v[170:173], v[186:189], v[96:99]
	v_mfma_f32_16x16x32_bf16 v[84:87], v[162:165], v[208:211], v[84:87]
	v_mfma_f32_16x16x32_bf16 v[80:83], v[170:173], v[208:211], v[80:83]
	v_mfma_f32_16x16x32_bf16 v[68:71], v[162:165], v[216:219], v[68:71]
	v_mfma_f32_16x16x32_bf16 v[64:67], v[170:173], v[216:219], v[64:67]
	s_setprio 0
	s_barrier
; #define PG8_STAGE(bufoff, gbase, voff) do { _Pragma("unroll") for (int _i = 0; _i < 2; ++_i) \
;         __builtin_amdgcn_global_load_lds((const unsigned*)((const char*)(gbase) + (voff)[_i]), (PG8_LAS unsigned*)(lds + (bufoff) + ldsw + _i * 8192), 16, 0, 0); } while (0)
; #define PG8_LDA(dst, b, h) do { _Pragma("unroll") for (int m = 0; m < 4; ++m) _Pragma("unroll") for (int k = 0; k < 2; ++k) dst[m][k] = *(const PG8_LAS bf16x8*)(lds + PG8_SA(b, h) + aoff + m * 2048 + k * 1024); } while (0)
; #define PG8_MMA(ai, bj, At, Bt) do { __builtin_amdgcn_s_setprio(1); _Pragma("unroll") for (int m = 0; m < 4; ++m) _Pragma("unroll") for (int n = 0; n < 2; ++n) _Pragma("unroll") for (int k = 0; k < 2; ++k) \
;         acc[ai][bj][m][n] = __builtin_amdgcn_mfma_f32_16x16x32_bf16(Bt[n][k], At[m][k], acc[ai][bj][m][n], 0, 0, 0); __builtin_amdgcn_s_setprio(0); } while (0)
; #define PG8_WAIT_V(n) asm volatile("s_waitcnt vmcnt(" #n ")" ::: "memory")
; #define PG8_WAIT_L(n) asm volatile("s_waitcnt lgkmcnt(" #n ")" ::: "memory")
; #define PG8_BAR __builtin_amdgcn_s_barrier()
; #define PG8_SCHED __builtin_amdgcn_sched_barrier(0)
; template <class Epi, class Sched, bool ALIGN_EPI = false, bool SP2 = false>
; __device__ __forceinline__ void gemm_phase(PG8_LAS unsigned char* lds, const Gemm g, const Sched& S, const Epi& E) {
;     ...
;         for (int t = 0; t < nt; t += 2) {
;     ...
;             PG8_LDA(At, 1, 1); PG8_STAGE(PG8_SB(1, 0), b3, voffB); PG8_STAGE(PG8_SB(1, 1), b3 + hstep, voffB); PG8_STAGE(PG8_SA(1, 0), a3, voffA);
;             PG8_WAIT_V(8); PG8_WAIT_L(0); PG8_BAR; PG8_MMA(1, 0, At, B0); PG8_MMA(1, 1, At, B1); PG8_BAR; PG8_SCHED;
	s_add_i32 s26, s50, s31
	v_lshl_add_u64 v[190:191], v[190:191], 0, s[90:91]
	s_mov_b32 m0, s26
	ds_read_b128 v[174:177], v141 offset:49152
	ds_read_b128 v[178:181], v141 offset:50176
	ds_read_b128 v[182:185], v141 offset:51200
	ds_read_b128 v[186:189], v141 offset:52224
	ds_read_b128 v[204:207], v141 offset:53248
	ds_read_b128 v[208:211], v141 offset:54272
	ds_read_b128 v[212:215], v141 offset:55296
	ds_read_b128 v[216:219], v141 offset:56320
	global_load_lds_dwordx4 v[190:191], off
	v_lshl_add_u64 v[190:191], v[194:195], 0, s[90:91]
	s_add_i32 m0, s26, 0x2000
	s_add_i32 s26, s51, s31
	global_load_lds_dwordx4 v[190:191], off
	v_lshl_add_u64 v[190:191], v[200:201], 0, s[90:91]
	s_mov_b32 m0, s26
	s_nop 0
	global_load_lds_dwordx4 v[190:191], off
	v_lshl_add_u64 v[190:191], v[202:203], 0, s[90:91]
	s_add_i32 m0, s26, 0x2000
	s_nop 0
	global_load_lds_dwordx4 v[190:191], off
	v_lshl_add_u64 v[190:191], v[220:221], 0, s[90:91]
	s_mov_b32 m0, s40
	s_nop 0
	global_load_lds_dwordx4 v[190:191], off
	v_lshl_add_u64 v[190:191], v[222:223], 0, s[90:91]
	s_mov_b32 m0, s41
	s_nop 0
	global_load_lds_dwordx4 v[190:191], off
	s_waitcnt vmcnt(8)
	s_waitcnt lgkmcnt(0)
	s_barrier
	s_setprio 1
	s_waitcnt lgkmcnt(0)
	v_mfma_f32_16x16x32_bf16 v[60:63], v[142:145], v[174:177], v[60:63]
	v_mfma_f32_16x16x32_bf16 v[56:59], v[150:153], v[174:177], v[56:59]
	v_mfma_f32_16x16x32_bf16 v[44:47], v[142:145], v[182:185], v[44:47]
	v_mfma_f32_16x16x32_bf16 v[40:43], v[150:153], v[182:185], v[40:43]
	v_mfma_f32_16x16x32_bf16 v[28:31], v[142:145], v[204:207], v[28:31]
	v_mfma_f32_16x16x32_bf16 v[24:27], v[150:153], v[204:207], v[24:27]
	v_mfma_f32_16x16x32_bf16 v[12:15], v[142:145], v[212:215], v[12:15]
	v_mfma_f32_16x16x32_bf16 v[8:11], v[150:153], v[212:215], v[8:11]
	v_mfma_f32_16x16x32_bf16 v[60:63], v[146:149], v[178:181], v[60:63]
	v_mfma_f32_16x16x32_bf16 v[56:59], v[154:157], v[178:181], v[56:59]
	v_mfma_f32_16x16x32_bf16 v[44:47], v[146:149], v[186:189], v[44:47]
	v_mfma_f32_16x16x32_bf16 v[40:43], v[154:157], v[186:189], v[40:43]
	v_mfma_f32_16x16x32_bf16 v[28:31], v[146:149], v[208:211], v[28:31]
	v_mfma_f32_16x16x32_bf16 v[24:27], v[154:157], v[208:211], v[24:27]
	v_mfma_f32_16x16x32_bf16 v[12:15], v[146:149], v[216:219], v[12:15]
	v_mfma_f32_16x16x32_bf16 v[8:11], v[154:157], v[216:219], v[8:11]
	s_setprio 0
	s_setprio 1
	v_mfma_f32_16x16x32_bf16 v[52:55], v[158:161], v[174:177], v[52:55]
	v_mfma_f32_16x16x32_bf16 v[48:51], v[166:169], v[174:177], v[48:51]
	v_mfma_f32_16x16x32_bf16 v[36:39], v[158:161], v[182:185], v[36:39]
	v_mfma_f32_16x16x32_bf16 v[32:35], v[166:169], v[182:185], v[32:35]
	v_mfma_f32_16x16x32_bf16 v[20:23], v[158:161], v[204:207], v[20:23]
	v_mfma_f32_16x16x32_bf16 v[16:19], v[166:169], v[204:207], v[16:19]
	v_mfma_f32_16x16x32_bf16 v[4:7], v[158:161], v[212:215], v[4:7]
	v_mfma_f32_16x16x32_bf16 v[0:3], v[166:169], v[212:215], v[0:3]
	v_mfma_f32_16x16x32_bf16 v[52:55], v[162:165], v[178:181], v[52:55]
	v_mfma_f32_16x16x32_bf16 v[48:51], v[170:173], v[178:181], v[48:51]
	v_mfma_f32_16x16x32_bf16 v[36:39], v[162:165], v[186:189], v[36:39]
	v_mfma_f32_16x16x32_bf16 v[32:35], v[170:173], v[186:189], v[32:35]
	v_mfma_f32_16x16x32_bf16 v[20:23], v[162:165], v[208:211], v[20:23]
	v_mfma_f32_16x16x32_bf16 v[16:19], v[170:173], v[208:211], v[16:19]
	v_mfma_f32_16x16x32_bf16 v[4:7], v[162:165], v[216:219], v[4:7]
	v_mfma_f32_16x16x32_bf16 v[0:3], v[170:173], v[216:219], v[0:3]
	s_setprio 0
	s_barrier
	s_add_u32 s24, s24, 0x100
	s_addc_u32 s25, s25, 0
	s_add_u32 s33, s33, 0x100
	s_addc_u32 s48, s48, 0
	s_cmp_ge_i32 s49, s38
	s_mov_b32 s26, s49
	s_cbranch_scc0 .LBB0_464
	s_branch .LBB0_465

; #define PG8_STAGE(bufoff, gbase, voff) do { _Pragma("unroll") for (int _i = 0; _i < 2; ++_i) \
;         __builtin_amdgcn_global_load_lds((const unsigned*)((const char*)(gbase) + (voff)[_i]), (PG8_LAS unsigned*)(lds + (bufoff) + ldsw + _i * 8192), 16, 0, 0); } while (0)
; #define PG8_LDA(dst, b, h) do { _Pragma("unroll") for (int m = 0; m < 4; ++m) _Pragma("unroll") for (int k = 0; k < 2; ++k) dst[m][k] = *(const PG8_LAS bf16x8*)(lds + PG8_SA(b, h) + aoff + m * 2048 + k * 1024); } while (0)
; #define PG8_LDB(dst, b, h) do { _Pragma("unroll") for (int n = 0; n < 2; ++n) _Pragma("unroll") for (int k = 0; k < 2; ++k) dst[n][k] = *(const PG8_LAS bf16x8*)(lds + PG8_SB(b, h) + boff + n * 2048 + k * 1024); } while (0)
; #define PG8_MMA(ai, bj, At, Bt) do { __builtin_amdgcn_s_setprio(1); _Pragma("unroll") for (int m = 0; m < 4; ++m) _Pragma("unroll") for (int n = 0; n < 2; ++n) _Pragma("unroll") for (int k = 0; k < 2; ++k) \
;         acc[ai][bj][m][n] = __builtin_amdgcn_mfma_f32_16x16x32_bf16(Bt[n][k], At[m][k], acc[ai][bj][m][n], 0, 0, 0); __builtin_amdgcn_s_setprio(0); } while (0)
; #define PG8_WAIT_V(n) asm volatile("s_waitcnt vmcnt(" #n ")" ::: "memory")
; #define PG8_WAIT_L(n) asm volatile("s_waitcnt lgkmcnt(" #n ")" ::: "memory")
; #define PG8_BAR __builtin_amdgcn_s_barrier()
; template <class Epi, class Sched, bool ALIGN_EPI = false, bool SP2 = false>
; __device__ __forceinline__ void gemm_phase(PG8_LAS unsigned char* lds, const Gemm g, const Sched& S, const Epi& E) {
;     ...
;             PG8_LDB(B0, 0, 0); PG8_LDB(B1, 0, 1); PG8_SCHED; PG8_LDA(At, 0, 0); PG8_STAGE(PG8_SA(1, 1), a1 + hstepA, voffA);
;             if (plast) PG8_WAIT_V(10); else PG8_WAIT_SEL(defer, 12, 16);
;             PG8_WAIT_L(0); PG8_BAR; PG8_MMA(0, 0, At, B0); PG8_MMA(0, 1, At, B1);
;             if constexpr (Epi::SPLIT) { if (defer) {
;                 E.second(acc, prev, rv1, wr, wc, fr, fq);
;                 _Pragma("unroll") for (int b = 0; b < 2; ++b) _Pragma("unroll") for (int m = 0; m < 4; ++m) _Pragma("unroll") for (int n = 0; n < 2; ++n) acc[1][b][m][n] = (f32x4){0.f, 0.f, 0.f, 0.f}; } }
;             PG8_BAR; PG8_SCHED;
;             PG8_LDA(At, 0, 1); PG8_STAGE(PG8_SB(0, 0), b2, voffB); PG8_STAGE(PG8_SB(0, 1), b2 + hstep, voffB); PG8_STAGE(PG8_SA(0, 0), a2, voffA);
;             if (plast) PG8_WAIT_V(10); else PG8_WAIT_SEL(defer, 16, 24);
.LBB0_495:
	s_andn2_b64 vcc, exec, s[20:21]
	s_cbranch_vccnz .Lzt_4
	s_add_u32 s0, s0, 0x80
	s_addc_u32 s1, s1, 0
	s_add_u32 s33, s26, 0x100
	s_addc_u32 s48, s27, 0
	s_mov_b32 s26, 0
.Lpk_dn_497:
	s_add_i32 s49, s26, 2
	s_add_u32 s50, s0, 0x80
	s_addc_u32 s27, s1, 0
	s_add_i32 s52, 0, 0x10000
	s_cmp_eq_u32 s43, s26
	s_cselect_b32 s27, s9, s27
	s_cselect_b32 s26, s8, s50
	s_cselect_b32 s51, s25, s48
	s_cselect_b32 s50, s24, s33
	s_add_i32 s53, 0, 0x14000
	v_add_u32_e32 v140, s52, v186
	v_add_u32_e32 v166, s53, v186
	ds_read_b128 v[128:131], v140
	ds_read_b128 v[132:135], v140 offset:1024
	ds_read_b128 v[136:139], v140 offset:2048
	ds_read_b128 v[140:143], v140 offset:3072
	ds_read_b128 v[144:147], v166
	ds_read_b128 v[148:151], v166 offset:1024
	ds_read_b128 v[152:155], v166 offset:2048
	ds_read_b128 v[166:169], v166 offset:3072
	v_lshl_add_u64 v[182:183], s[0:1], 0, v[162:163]
	s_add_i32 m0, s31, 0xc000
	ds_read_b128 v[170:173], v187
	ds_read_b128 v[174:177], v187 offset:1024
	ds_read_b128 v[178:181], v187 offset:2048
	ds_read_b128 v[188:191], v187 offset:3072
	ds_read_b128 v[204:207], v187 offset:4096
	ds_read_b128 v[208:211], v187 offset:5120
	ds_read_b128 v[212:215], v187 offset:6144
	ds_read_b128 v[216:219], v187 offset:7168
	global_load_lds_dwordx4 v[182:183], off
	v_lshl_add_u64 v[182:183], s[0:1], 0, v[164:165]
	s_add_i32 m0, s31, 0xe000
	s_nop 0
	global_load_lds_dwordx4 v[182:183], off
	s_waitcnt vmcnt(8)
	s_waitcnt lgkmcnt(0)
	s_barrier
	s_setprio 1
	s_waitcnt lgkmcnt(0)
	v_mfma_f32_16x16x32_bf16 v[120:123], v[128:131], v[170:173], 0
	v_mfma_f32_16x16x32_bf16 v[124:127], v[136:139], v[170:173], 0
	v_mfma_f32_16x16x32_bf16 v[108:111], v[128:131], v[178:181], 0
	v_mfma_f32_16x16x32_bf16 v[104:107], v[136:139], v[178:181], 0
	v_mfma_f32_16x16x32_bf16 v[92:95], v[128:131], v[204:207], 0
	v_mfma_f32_16x16x32_bf16 v[88:91], v[136:139], v[204:207], 0
	v_mfma_f32_16x16x32_bf16 v[76:79], v[128:131], v[212:215], 0
	v_mfma_f32_16x16x32_bf16 v[72:75], v[136:139], v[212:215], 0
	v_mfma_f32_16x16x32_bf16 v[120:123], v[132:135], v[174:177], v[120:123]
	v_mfma_f32_16x16x32_bf16 v[124:127], v[140:143], v[174:177], v[124:127]
	v_mfma_f32_16x16x32_bf16 v[108:111], v[132:135], v[188:191], v[108:111]
	v_mfma_f32_16x16x32_bf16 v[104:107], v[140:143], v[188:191], v[104:107]
	v_mfma_f32_16x16x32_bf16 v[92:95], v[132:135], v[208:211], v[92:95]
	v_mfma_f32_16x16x32_bf16 v[88:91], v[140:143], v[208:211], v[88:91]
	v_mfma_f32_16x16x32_bf16 v[76:79], v[132:135], v[216:219], v[76:79]
	v_mfma_f32_16x16x32_bf16 v[72:75], v[140:143], v[216:219], v[72:75]
	s_setprio 0
	s_setprio 1
	v_mfma_f32_16x16x32_bf16 v[116:119], v[144:147], v[170:173], 0
	v_mfma_f32_16x16x32_bf16 v[112:115], v[152:155], v[170:173], 0
	v_mfma_f32_16x16x32_bf16 v[100:103], v[144:147], v[178:181], 0
	v_mfma_f32_16x16x32_bf16 v[96:99], v[152:155], v[178:181], 0
	v_mfma_f32_16x16x32_bf16 v[84:87], v[144:147], v[204:207], 0
	v_mfma_f32_16x16x32_bf16 v[80:83], v[152:155], v[204:207], 0
	v_mfma_f32_16x16x32_bf16 v[68:71], v[144:147], v[212:215], 0
	v_mfma_f32_16x16x32_bf16 v[64:67], v[152:155], v[212:215], 0
	v_mfma_f32_16x16x32_bf16 v[116:119], v[148:151], v[174:177], v[116:119]
	v_mfma_f32_16x16x32_bf16 v[112:115], v[166:169], v[174:177], v[112:115]
	v_mfma_f32_16x16x32_bf16 v[100:103], v[148:151], v[188:191], v[100:103]
	v_mfma_f32_16x16x32_bf16 v[96:99], v[166:169], v[188:191], v[96:99]
	v_mfma_f32_16x16x32_bf16 v[84:87], v[148:151], v[208:211], v[84:87]
	v_mfma_f32_16x16x32_bf16 v[80:83], v[166:169], v[208:211], v[80:83]
	v_mfma_f32_16x16x32_bf16 v[68:71], v[148:151], v[216:219], v[68:71]
	v_mfma_f32_16x16x32_bf16 v[64:67], v[166:169], v[216:219], v[64:67]
	s_setprio 0
	s_barrier
	s_add_i32 s52, s52, s30
	v_lshl_add_u64 v[182:183], s[50:51], 0, v[192:193]
	s_mov_b32 m0, s52
	ds_read_b128 v[170:173], v187 offset:16384
	ds_read_b128 v[174:177], v187 offset:17408
	ds_read_b128 v[178:181], v187 offset:18432
	ds_read_b128 v[188:191], v187 offset:19456
	ds_read_b128 v[204:207], v187 offset:20480
	ds_read_b128 v[208:211], v187 offset:21504
	ds_read_b128 v[212:215], v187 offset:22528
	ds_read_b128 v[216:219], v187 offset:23552
	global_load_lds_dwordx4 v[182:183], off
	s_add_i32 m0, s52, 0x2000
	v_lshl_add_u64 v[194:195], s[50:51], 0, v[156:157]
	s_add_u32 s50, s50, s14
	s_addc_u32 s51, s51, s15
	s_add_i32 s52, s53, s30
	global_load_lds_dwordx4 v[194:195], off
	v_lshl_add_u64 v[200:201], s[50:51], 0, v[192:193]
	s_mov_b32 m0, s52
	v_lshl_add_u64 v[202:203], s[50:51], 0, v[156:157]
	global_load_lds_dwordx4 v[200:201], off
	s_add_i32 m0, s52, 0x2000
	v_lshl_add_u64 v[220:221], s[26:27], 0, v[160:161]
	global_load_lds_dwordx4 v[202:203], off
	s_mov_b32 m0, s31
	v_lshl_add_u64 v[222:223], s[26:27], 0, v[158:159]
	global_load_lds_dwordx4 v[220:221], off
	s_mov_b32 m0, s34
	s_nop 0
	global_load_lds_dwordx4 v[222:223], off
	s_waitcnt vmcnt(8)
	s_waitcnt lgkmcnt(0)
	s_barrier
; #define PG8_STAGE(bufoff, gbase, voff) do { _Pragma("unroll") for (int _i = 0; _i < 2; ++_i) \
;         __builtin_amdgcn_global_load_lds((const unsigned*)((const char*)(gbase) + (voff)[_i]), (PG8_LAS unsigned*)(lds + (bufoff) + ldsw + _i * 8192), 16, 0, 0); } while (0)
; #define PG8_LDA(dst, b, h) do { _Pragma("unroll") for (int m = 0; m < 4; ++m) _Pragma("unroll") for (int k = 0; k < 2; ++k) dst[m][k] = *(const PG8_LAS bf16x8*)(lds + PG8_SA(b, h) + aoff + m * 2048 + k * 1024); } while (0)
; #define PG8_LDB(dst, b, h) do { _Pragma("unroll") for (int n = 0; n < 2; ++n) _Pragma("unroll") for (int k = 0; k < 2; ++k) dst[n][k] = *(const PG8_LAS bf16x8*)(lds + PG8_SB(b, h) + boff + n * 2048 + k * 1024); } while (0)
; #define PG8_MMA(ai, bj, At, Bt) do { __builtin_amdgcn_s_setprio(1); _Pragma("unroll") for (int m = 0; m < 4; ++m) _Pragma("unroll") for (int n = 0; n < 2; ++n) _Pragma("unroll") for (int k = 0; k < 2; ++k) \
;         acc[ai][bj][m][n] = __builtin_amdgcn_mfma_f32_16x16x32_bf16(Bt[n][k], At[m][k], acc[ai][bj][m][n], 0, 0, 0); __builtin_amdgcn_s_setprio(0); } while (0)
; #define PG8_WAIT_SEL(d, w4, w8) do { if constexpr (Epi::SPLIT) { if (d) { if constexpr (Epi::NSH == 4) PG8_WAIT_V(w4); else PG8_WAIT_V(w8); } else PG8_WAIT_V(8); } else PG8_WAIT_V(8); } while (0)
; #define PG8_WAIT_L(n) asm volatile("s_waitcnt lgkmcnt(" #n ")" ::: "memory")
; #define PG8_BAR __builtin_amdgcn_s_barrier()
; #define PG8_SCHED __builtin_amdgcn_sched_barrier(0)
; template <class Epi, class Sched, bool ALIGN_EPI = false, bool SP2 = false>
; __device__ __forceinline__ void gemm_phase(PG8_LAS unsigned char* lds, const Gemm g, const Sched& S, const Epi& E) {
;     ...
;             PG8_WAIT_L(0); PG8_BAR; PG8_MMA(1, 0, At, B0); PG8_MMA(1, 1, At, B1); PG8_BAR; PG8_SCHED;
;             PG8_LDB(B0, 1, 0); PG8_LDB(B1, 1, 1); PG8_SCHED; PG8_LDA(At, 1, 0); PG8_STAGE(PG8_SA(0, 1), a2 + hstepA, voffA);
;             PG8_WAIT_SEL(defer, 12, 16); PG8_WAIT_L(0); PG8_BAR; PG8_MMA(0, 0, At, B0); PG8_MMA(0, 1, At, B1); PG8_BAR; PG8_SCHED;
	s_setprio 1
	s_waitcnt lgkmcnt(0)
	v_mfma_f32_16x16x32_bf16 v[60:63], v[128:131], v[170:173], 0
	v_mfma_f32_16x16x32_bf16 v[56:59], v[136:139], v[170:173], 0
	v_mfma_f32_16x16x32_bf16 v[44:47], v[128:131], v[178:181], 0
	v_mfma_f32_16x16x32_bf16 v[40:43], v[136:139], v[178:181], 0
	v_mfma_f32_16x16x32_bf16 v[28:31], v[128:131], v[204:207], 0
	v_mfma_f32_16x16x32_bf16 v[24:27], v[136:139], v[204:207], 0
	v_mfma_f32_16x16x32_bf16 v[12:15], v[128:131], v[212:215], 0
	v_mfma_f32_16x16x32_bf16 v[8:11], v[136:139], v[212:215], 0
	v_mfma_f32_16x16x32_bf16 v[60:63], v[132:135], v[174:177], v[60:63]
	v_mfma_f32_16x16x32_bf16 v[56:59], v[140:143], v[174:177], v[56:59]
	v_mfma_f32_16x16x32_bf16 v[44:47], v[132:135], v[188:191], v[44:47]
	v_mfma_f32_16x16x32_bf16 v[40:43], v[140:143], v[188:191], v[40:43]
	v_mfma_f32_16x16x32_bf16 v[28:31], v[132:135], v[208:211], v[28:31]
	v_mfma_f32_16x16x32_bf16 v[24:27], v[140:143], v[208:211], v[24:27]
	v_mfma_f32_16x16x32_bf16 v[12:15], v[132:135], v[216:219], v[12:15]
	v_mfma_f32_16x16x32_bf16 v[8:11], v[140:143], v[216:219], v[8:11]
	s_setprio 0
	s_setprio 1
	v_mfma_f32_16x16x32_bf16 v[52:55], v[144:147], v[170:173], 0
	v_mfma_f32_16x16x32_bf16 v[48:51], v[152:155], v[170:173], 0
	v_mfma_f32_16x16x32_bf16 v[36:39], v[144:147], v[178:181], 0
	v_mfma_f32_16x16x32_bf16 v[32:35], v[152:155], v[178:181], 0
	v_mfma_f32_16x16x32_bf16 v[20:23], v[144:147], v[204:207], 0
	v_mfma_f32_16x16x32_bf16 v[16:19], v[152:155], v[204:207], 0
	v_mfma_f32_16x16x32_bf16 v[4:7], v[144:147], v[212:215], 0
	v_mfma_f32_16x16x32_bf16 v[0:3], v[152:155], v[212:215], 0
	v_mfma_f32_16x16x32_bf16 v[52:55], v[148:151], v[174:177], v[52:55]
	v_mfma_f32_16x16x32_bf16 v[48:51], v[166:169], v[174:177], v[48:51]
	v_mfma_f32_16x16x32_bf16 v[36:39], v[148:151], v[188:191], v[36:39]
	v_mfma_f32_16x16x32_bf16 v[32:35], v[166:169], v[188:191], v[32:35]
	v_mfma_f32_16x16x32_bf16 v[20:23], v[148:151], v[208:211], v[20:23]
	v_mfma_f32_16x16x32_bf16 v[16:19], v[166:169], v[208:211], v[16:19]
	v_mfma_f32_16x16x32_bf16 v[4:7], v[148:151], v[216:219], v[4:7]
	v_mfma_f32_16x16x32_bf16 v[0:3], v[166:169], v[216:219], v[0:3]
	s_setprio 0
	s_barrier
	s_add_i32 s50, 0, 0x18000
	s_add_i32 s51, 0, 0x1c000
	v_add_u32_e32 v140, s50, v186
	v_add_u32_e32 v166, s51, v186
	ds_read_b128 v[128:131], v140
	ds_read_b128 v[132:135], v140 offset:1024
	ds_read_b128 v[136:139], v140 offset:2048
	ds_read_b128 v[140:143], v140 offset:3072
	ds_read_b128 v[144:147], v166
	ds_read_b128 v[148:151], v166 offset:1024
	ds_read_b128 v[152:155], v166 offset:2048
	ds_read_b128 v[166:169], v166 offset:3072
	s_add_u32 s26, s26, s10
	s_addc_u32 s27, s27, s11
	s_mov_b32 m0, s35
	v_lshl_add_u64 v[224:225], s[26:27], 0, v[160:161]
	ds_read_b128 v[170:173], v187 offset:32768
	ds_read_b128 v[174:177], v187 offset:33792
	ds_read_b128 v[178:181], v187 offset:34816
	ds_read_b128 v[188:191], v187 offset:35840
	ds_read_b128 v[204:207], v187 offset:36864
	ds_read_b128 v[208:211], v187 offset:37888
	ds_read_b128 v[212:215], v187 offset:38912
	ds_read_b128 v[216:219], v187 offset:39936
	global_load_lds_dwordx4 v[224:225], off
	v_lshl_add_u64 v[224:225], s[26:27], 0, v[158:159]
	s_mov_b32 m0, s36
	s_nop 0
	global_load_lds_dwordx4 v[224:225], off
	s_waitcnt vmcnt(8)
	s_waitcnt lgkmcnt(0)
	s_barrier
	s_setprio 1
	s_waitcnt lgkmcnt(0)
	v_mfma_f32_16x16x32_bf16 v[120:123], v[128:131], v[170:173], v[120:123]
	v_mfma_f32_16x16x32_bf16 v[124:127], v[136:139], v[170:173], v[124:127]
	v_mfma_f32_16x16x32_bf16 v[108:111], v[128:131], v[178:181], v[108:111]
	v_mfma_f32_16x16x32_bf16 v[104:107], v[136:139], v[178:181], v[104:107]
	v_mfma_f32_16x16x32_bf16 v[92:95], v[128:131], v[204:207], v[92:95]
	v_mfma_f32_16x16x32_bf16 v[88:91], v[136:139], v[204:207], v[88:91]
	v_mfma_f32_16x16x32_bf16 v[76:79], v[128:131], v[212:215], v[76:79]
	v_mfma_f32_16x16x32_bf16 v[72:75], v[136:139], v[212:215], v[72:75]
	v_mfma_f32_16x16x32_bf16 v[120:123], v[132:135], v[174:177], v[120:123]
	v_mfma_f32_16x16x32_bf16 v[124:127], v[140:143], v[174:177], v[124:127]
	v_mfma_f32_16x16x32_bf16 v[108:111], v[132:135], v[188:191], v[108:111]
	v_mfma_f32_16x16x32_bf16 v[104:107], v[140:143], v[188:191], v[104:107]
	v_mfma_f32_16x16x32_bf16 v[92:95], v[132:135], v[208:211], v[92:95]
	v_mfma_f32_16x16x32_bf16 v[88:91], v[140:143], v[208:211], v[88:91]
	v_mfma_f32_16x16x32_bf16 v[76:79], v[132:135], v[216:219], v[76:79]
	v_mfma_f32_16x16x32_bf16 v[72:75], v[140:143], v[216:219], v[72:75]
	s_setprio 0
	s_setprio 1
	v_mfma_f32_16x16x32_bf16 v[116:119], v[144:147], v[170:173], v[116:119]
	v_mfma_f32_16x16x32_bf16 v[112:115], v[152:155], v[170:173], v[112:115]
	v_mfma_f32_16x16x32_bf16 v[100:103], v[144:147], v[178:181], v[100:103]
	v_mfma_f32_16x16x32_bf16 v[96:99], v[152:155], v[178:181], v[96:99]
	v_mfma_f32_16x16x32_bf16 v[84:87], v[144:147], v[204:207], v[84:87]
	v_mfma_f32_16x16x32_bf16 v[80:83], v[152:155], v[204:207], v[80:83]
	v_mfma_f32_16x16x32_bf16 v[68:71], v[144:147], v[212:215], v[68:71]
	v_mfma_f32_16x16x32_bf16 v[64:67], v[152:155], v[212:215], v[64:67]
	v_mfma_f32_16x16x32_bf16 v[116:119], v[148:151], v[174:177], v[116:119]
	v_mfma_f32_16x16x32_bf16 v[112:115], v[166:169], v[174:177], v[112:115]
	v_mfma_f32_16x16x32_bf16 v[100:103], v[148:151], v[188:191], v[100:103]
	v_mfma_f32_16x16x32_bf16 v[96:99], v[166:169], v[188:191], v[96:99]
	v_mfma_f32_16x16x32_bf16 v[84:87], v[148:151], v[208:211], v[84:87]
	v_mfma_f32_16x16x32_bf16 v[80:83], v[166:169], v[208:211], v[80:83]
	v_mfma_f32_16x16x32_bf16 v[68:71], v[148:151], v[216:219], v[68:71]
	v_mfma_f32_16x16x32_bf16 v[64:67], v[166:169], v[216:219], v[64:67]
	s_setprio 0
	s_barrier
; #define PG8_STAGE(bufoff, gbase, voff) do { _Pragma("unroll") for (int _i = 0; _i < 2; ++_i) \
;         __builtin_amdgcn_global_load_lds((const unsigned*)((const char*)(gbase) + (voff)[_i]), (PG8_LAS unsigned*)(lds + (bufoff) + ldsw + _i * 8192), 16, 0, 0); } while (0)
; #define PG8_LDA(dst, b, h) do { _Pragma("unroll") for (int m = 0; m < 4; ++m) _Pragma("unroll") for (int k = 0; k < 2; ++k) dst[m][k] = *(const PG8_LAS bf16x8*)(lds + PG8_SA(b, h) + aoff + m * 2048 + k * 1024); } while (0)
; #define PG8_MMA(ai, bj, At, Bt) do { __builtin_amdgcn_s_setprio(1); _Pragma("unroll") for (int m = 0; m < 4; ++m) _Pragma("unroll") for (int n = 0; n < 2; ++n) _Pragma("unroll") for (int k = 0; k < 2; ++k) \
;         acc[ai][bj][m][n] = __builtin_amdgcn_mfma_f32_16x16x32_bf16(Bt[n][k], At[m][k], acc[ai][bj][m][n], 0, 0, 0); __builtin_amdgcn_s_setprio(0); } while (0)
; #define PG8_WAIT_V(n) asm volatile("s_waitcnt vmcnt(" #n ")" ::: "memory")
; #define PG8_WAIT_L(n) asm volatile("s_waitcnt lgkmcnt(" #n ")" ::: "memory")
; #define PG8_BAR __builtin_amdgcn_s_barrier()
; #define PG8_SCHED __builtin_amdgcn_sched_barrier(0)
; template <class Epi, class Sched, bool ALIGN_EPI = false, bool SP2 = false>
; __device__ __forceinline__ void gemm_phase(PG8_LAS unsigned char* lds, const Gemm g, const Sched& S, const Epi& E) {
;     ...
;         for (int t = 0; t < nt; t += 2) {
;     ...
;             PG8_LDA(At, 1, 1); PG8_STAGE(PG8_SB(1, 0), b3, voffB); PG8_STAGE(PG8_SB(1, 1), b3 + hstep, voffB); PG8_STAGE(PG8_SA(1, 0), a3, voffA);
;             PG8_WAIT_V(8); PG8_WAIT_L(0); PG8_BAR; PG8_MMA(1, 0, At, B0); PG8_MMA(1, 1, At, B1); PG8_BAR; PG8_SCHED;
	s_add_i32 s26, s50, s30
	v_lshl_add_u64 v[182:183], v[182:183], 0, s[90:91]
	s_mov_b32 m0, s26
	ds_read_b128 v[170:173], v187 offset:49152
	ds_read_b128 v[174:177], v187 offset:50176
	ds_read_b128 v[178:181], v187 offset:51200
	ds_read_b128 v[188:191], v187 offset:52224
	ds_read_b128 v[204:207], v187 offset:53248
	ds_read_b128 v[208:211], v187 offset:54272
	ds_read_b128 v[212:215], v187 offset:55296
	ds_read_b128 v[216:219], v187 offset:56320
	global_load_lds_dwordx4 v[182:183], off
	v_lshl_add_u64 v[182:183], v[194:195], 0, s[90:91]
	s_add_i32 m0, s26, 0x2000
	s_add_i32 s26, s51, s30
	global_load_lds_dwordx4 v[182:183], off
	v_lshl_add_u64 v[182:183], v[200:201], 0, s[90:91]
	s_mov_b32 m0, s26
	s_nop 0
	global_load_lds_dwordx4 v[182:183], off
	v_lshl_add_u64 v[182:183], v[202:203], 0, s[90:91]
	s_add_i32 m0, s26, 0x2000
	s_nop 0
	global_load_lds_dwordx4 v[182:183], off
	v_lshl_add_u64 v[182:183], v[220:221], 0, s[90:91]
	s_mov_b32 m0, s41
	s_nop 0
	global_load_lds_dwordx4 v[182:183], off
	v_lshl_add_u64 v[182:183], v[222:223], 0, s[90:91]
	s_mov_b32 m0, s42
	s_nop 0
	global_load_lds_dwordx4 v[182:183], off
	s_waitcnt vmcnt(8)
	s_waitcnt lgkmcnt(0)
	s_barrier
	s_setprio 1
	s_waitcnt lgkmcnt(0)
	v_mfma_f32_16x16x32_bf16 v[60:63], v[128:131], v[170:173], v[60:63]
	v_mfma_f32_16x16x32_bf16 v[56:59], v[136:139], v[170:173], v[56:59]
	v_mfma_f32_16x16x32_bf16 v[44:47], v[128:131], v[178:181], v[44:47]
	v_mfma_f32_16x16x32_bf16 v[40:43], v[136:139], v[178:181], v[40:43]
	v_mfma_f32_16x16x32_bf16 v[28:31], v[128:131], v[204:207], v[28:31]
	v_mfma_f32_16x16x32_bf16 v[24:27], v[136:139], v[204:207], v[24:27]
	v_mfma_f32_16x16x32_bf16 v[12:15], v[128:131], v[212:215], v[12:15]
	v_mfma_f32_16x16x32_bf16 v[8:11], v[136:139], v[212:215], v[8:11]
	v_mfma_f32_16x16x32_bf16 v[60:63], v[132:135], v[174:177], v[60:63]
	v_mfma_f32_16x16x32_bf16 v[56:59], v[140:143], v[174:177], v[56:59]
	v_mfma_f32_16x16x32_bf16 v[44:47], v[132:135], v[188:191], v[44:47]
	v_mfma_f32_16x16x32_bf16 v[40:43], v[140:143], v[188:191], v[40:43]
	v_mfma_f32_16x16x32_bf16 v[28:31], v[132:135], v[208:211], v[28:31]
	v_mfma_f32_16x16x32_bf16 v[24:27], v[140:143], v[208:211], v[24:27]
	v_mfma_f32_16x16x32_bf16 v[12:15], v[132:135], v[216:219], v[12:15]
	v_mfma_f32_16x16x32_bf16 v[8:11], v[140:143], v[216:219], v[8:11]
	s_setprio 0
	s_setprio 1
	v_mfma_f32_16x16x32_bf16 v[52:55], v[144:147], v[170:173], v[52:55]
	v_mfma_f32_16x16x32_bf16 v[48:51], v[152:155], v[170:173], v[48:51]
	v_mfma_f32_16x16x32_bf16 v[36:39], v[144:147], v[178:181], v[36:39]
	v_mfma_f32_16x16x32_bf16 v[32:35], v[152:155], v[178:181], v[32:35]
	v_mfma_f32_16x16x32_bf16 v[20:23], v[144:147], v[204:207], v[20:23]
	v_mfma_f32_16x16x32_bf16 v[16:19], v[152:155], v[204:207], v[16:19]
	v_mfma_f32_16x16x32_bf16 v[4:7], v[144:147], v[212:215], v[4:7]
	v_mfma_f32_16x16x32_bf16 v[0:3], v[152:155], v[212:215], v[0:3]
	v_mfma_f32_16x16x32_bf16 v[52:55], v[148:151], v[174:177], v[52:55]
	v_mfma_f32_16x16x32_bf16 v[48:51], v[166:169], v[174:177], v[48:51]
	v_mfma_f32_16x16x32_bf16 v[36:39], v[148:151], v[188:191], v[36:39]
	v_mfma_f32_16x16x32_bf16 v[32:35], v[166:169], v[188:191], v[32:35]
	v_mfma_f32_16x16x32_bf16 v[20:23], v[148:151], v[208:211], v[20:23]
	v_mfma_f32_16x16x32_bf16 v[16:19], v[166:169], v[208:211], v[16:19]
	v_mfma_f32_16x16x32_bf16 v[4:7], v[148:151], v[216:219], v[4:7]
	v_mfma_f32_16x16x32_bf16 v[0:3], v[166:169], v[216:219], v[0:3]
	s_setprio 0
	s_barrier
	s_add_u32 s0, s0, 0x100
	s_addc_u32 s1, s1, 0
	s_add_u32 s33, s33, 0x100
	s_addc_u32 s48, s48, 0
	s_cmp_ge_i32 s49, s38
	s_mov_b32 s26, s49
	s_cbranch_scc0 .LBB0_497
	s_branch .LBB0_498

; #define PG8_LAS __attribute__((address_space(3)))
; template <class Epi, class Sched, bool ALIGN_EPI = false, bool SP2 = false>
; __device__ __forceinline__ void gemm_phase(PG8_LAS unsigned char* lds, const Gemm g, const Sched& S, const Epi& E) {
;     ...
;                 const char* pg = (const char*)E.part_in + (size_t)cur.pm * 16384 + (size_t)tid * 16;
;                 __builtin_amdgcn_global_load_lds((const unsigned*)pg, (PG8_LAS unsigned*)(lds + STAGE_BYTES + ldsw), 16, 0, 0);
;                 __builtin_amdgcn_global_load_lds((const unsigned*)(pg + 8192), (PG8_LAS unsigned*)(lds + STAGE_BYTES + 8192 + ldsw), 16, 0, 0); } }
;     ...
; #pragma unroll
;         for (int a = 0; a < (Epi::SPLIT ? 1 : 2); ++a)
; #pragma unroll
;             for (int b = 0; b < 2; ++b)
; #pragma unroll
;                 for (int m = 0; m < 4; ++m)
; #pragma unroll
;                     for (int n = 0; n < 2; ++n) acc[a][b][m][n] = (f32x4){0.f, 0.f, 0.f, 0.f};
.LBB0_558:
	s_andn2_b64 vcc, exec, s[22:23]
	s_cbranch_vccnz .Lzt_5
	s_ashr_i32 s1, s0, 31
	s_lshl_b64 s[34:35], s[0:1], 14
	s_add_u32 s28, s28, 0x80
	s_addc_u32 s29, s29, 0
	v_lshl_add_u64 v[216:217], v[210:211], 0, s[34:35]
	s_mov_b64 s[34:35], 0x2000
	s_add_u32 s1, s30, 0x100
	v_lshl_add_u64 v[218:219], v[216:217], 0, s[34:35]
	s_addc_u32 s33, s31, 0
	s_mov_b32 s59, 0

; #define PG8_STAGE(bufoff, gbase, voff) do { _Pragma("unroll") for (int _i = 0; _i < 2; ++_i) \
;         __builtin_amdgcn_global_load_lds((const unsigned*)((const char*)(gbase) + (voff)[_i]), (PG8_LAS unsigned*)(lds + (bufoff) + ldsw + _i * 8192), 16, 0, 0); } while (0)
; #define PG8_LDA(dst, b, h) do { _Pragma("unroll") for (int m = 0; m < 4; ++m) _Pragma("unroll") for (int k = 0; k < 2; ++k) dst[m][k] = *(const PG8_LAS bf16x8*)(lds + PG8_SA(b, h) + aoff + m * 2048 + k * 1024); } while (0)
; #define PG8_MMA(ai, bj, At, Bt) do { __builtin_amdgcn_s_setprio(1); _Pragma("unroll") for (int m = 0; m < 4; ++m) _Pragma("unroll") for (int n = 0; n < 2; ++n) _Pragma("unroll") for (int k = 0; k < 2; ++k) \
;         acc[ai][bj][m][n] = __builtin_amdgcn_mfma_f32_16x16x32_bf16(Bt[n][k], At[m][k], acc[ai][bj][m][n], 0, 0, 0); __builtin_amdgcn_s_setprio(0); } while (0)
; #define PG8_WAIT_V(n) asm volatile("s_waitcnt vmcnt(" #n ")" ::: "memory")
; #define PG8_WAIT_SEL(d, w4, w8) do { if constexpr (Epi::SPLIT) { if (d) { if constexpr (Epi::NSH == 4) PG8_WAIT_V(w4); else PG8_WAIT_V(w8); } else PG8_WAIT_V(8); } else PG8_WAIT_V(8); } while (0)
; #define PG8_WAIT_L(n) asm volatile("s_waitcnt lgkmcnt(" #n ")" ::: "memory")
; #define PG8_BAR __builtin_amdgcn_s_barrier()
; #define PG8_SCHED __builtin_amdgcn_sched_barrier(0)
; template <class Epi, class Sched, bool ALIGN_EPI = false, bool SP2 = false>
; __device__ __forceinline__ void gemm_phase(PG8_LAS unsigned char* lds, const Gemm g, const Sched& S, const Epi& E) {
;     ...
;             PG8_WAIT_L(0); PG8_BAR; PG8_MMA(0, 0, At, B0); PG8_MMA(0, 1, At, B1);
;             if constexpr (Epi::SPLIT) { if (defer) {
;                 E.second(acc, prev, rv1, wr, wc, fr, fq);
;                 _Pragma("unroll") for (int b = 0; b < 2; ++b) _Pragma("unroll") for (int m = 0; m < 4; ++m) _Pragma("unroll") for (int n = 0; n < 2; ++n) acc[1][b][m][n] = (f32x4){0.f, 0.f, 0.f, 0.f}; } }
;             PG8_BAR; PG8_SCHED;
;             PG8_LDA(At, 0, 1); PG8_STAGE(PG8_SB(0, 0), b2, voffB); PG8_STAGE(PG8_SB(0, 1), b2 + hstep, voffB); PG8_STAGE(PG8_SA(0, 0), a2, voffA);
;             if (plast) PG8_WAIT_V(10); else PG8_WAIT_SEL(defer, 16, 24);
.Lpk_pg_567:
	s_add_u32 s36, s28, 0x80
	s_addc_u32 s37, s29, 0
	s_waitcnt lgkmcnt(0)
	s_and_b64 s[30:31], s[30:31], exec
	s_cselect_b32 s31, s7, s37
	s_cselect_b32 s30, s6, s36
	s_cselect_b32 s37, s27, s33
	s_cselect_b32 s36, s26, s1
	s_barrier
	s_setprio 1
	s_waitcnt lgkmcnt(0)
	v_mfma_f32_16x16x32_bf16 v[124:127], v[144:147], v[184:187], 0
	v_mfma_f32_16x16x32_bf16 v[120:123], v[152:155], v[184:187], 0
	v_mfma_f32_16x16x32_bf16 v[108:111], v[144:147], v[176:179], 0
	v_mfma_f32_16x16x32_bf16 v[104:107], v[152:155], v[176:179], 0
	v_mfma_f32_16x16x32_bf16 v[92:95], v[144:147], v[168:171], 0
	v_mfma_f32_16x16x32_bf16 v[88:91], v[152:155], v[168:171], 0
	v_mfma_f32_16x16x32_bf16 v[76:79], v[144:147], v[160:163], 0
	v_mfma_f32_16x16x32_bf16 v[72:75], v[152:155], v[160:163], 0
	v_mfma_f32_16x16x32_bf16 v[124:127], v[148:151], v[188:191], v[124:127]
	v_mfma_f32_16x16x32_bf16 v[120:123], v[156:159], v[188:191], v[120:123]
	v_mfma_f32_16x16x32_bf16 v[108:111], v[148:151], v[180:183], v[108:111]
	v_mfma_f32_16x16x32_bf16 v[104:107], v[156:159], v[180:183], v[104:107]
	v_mfma_f32_16x16x32_bf16 v[92:95], v[148:151], v[172:175], v[92:95]
	v_mfma_f32_16x16x32_bf16 v[88:91], v[156:159], v[172:175], v[88:91]
	v_mfma_f32_16x16x32_bf16 v[76:79], v[148:151], v[164:167], v[76:79]
	v_mfma_f32_16x16x32_bf16 v[72:75], v[156:159], v[164:167], v[72:75]
	s_setprio 0
	s_setprio 1
	v_mfma_f32_16x16x32_bf16 v[116:119], v[128:131], v[184:187], 0
	v_mfma_f32_16x16x32_bf16 v[112:115], v[136:139], v[184:187], 0
	v_mfma_f32_16x16x32_bf16 v[100:103], v[128:131], v[176:179], 0
	v_mfma_f32_16x16x32_bf16 v[96:99], v[136:139], v[176:179], 0
	v_mfma_f32_16x16x32_bf16 v[84:87], v[128:131], v[168:171], 0
	v_mfma_f32_16x16x32_bf16 v[80:83], v[136:139], v[168:171], 0
	v_mfma_f32_16x16x32_bf16 v[68:71], v[128:131], v[160:163], 0
	v_mfma_f32_16x16x32_bf16 v[64:67], v[136:139], v[160:163], 0
	v_mfma_f32_16x16x32_bf16 v[116:119], v[132:135], v[188:191], v[116:119]
	v_mfma_f32_16x16x32_bf16 v[112:115], v[140:143], v[188:191], v[112:115]
	v_mfma_f32_16x16x32_bf16 v[100:103], v[132:135], v[180:183], v[100:103]
	v_mfma_f32_16x16x32_bf16 v[96:99], v[140:143], v[180:183], v[96:99]
	v_mfma_f32_16x16x32_bf16 v[84:87], v[132:135], v[172:175], v[84:87]
	v_mfma_f32_16x16x32_bf16 v[80:83], v[140:143], v[172:175], v[80:83]
	v_mfma_f32_16x16x32_bf16 v[68:71], v[132:135], v[164:167], v[68:71]
	v_mfma_f32_16x16x32_bf16 v[64:67], v[140:143], v[164:167], v[64:67]
	s_setprio 0
	s_barrier
	s_mov_b32 m0, s42
	v_lshl_add_u64 v[222:223], s[36:37], 0, v[192:193]
	v_lshl_add_u64 v[220:221], s[36:37], 0, v[204:205]
	s_add_u32 s36, s36, s12
	ds_read_b128 v[184:187], v240 offset:16384
	ds_read_b128 v[188:191], v240 offset:17408
	ds_read_b128 v[176:179], v240 offset:18432
	ds_read_b128 v[180:183], v240 offset:19456
	ds_read_b128 v[168:171], v240 offset:20480
	ds_read_b128 v[172:175], v240 offset:21504
	ds_read_b128 v[160:163], v240 offset:22528
	ds_read_b128 v[164:167], v240 offset:23552
	global_load_lds_dwordx4 v[222:223], off
	s_mov_b32 m0, s43
	s_addc_u32 s37, s37, s13
	global_load_lds_dwordx4 v[220:221], off
	v_lshl_add_u64 v[230:231], s[36:37], 0, v[192:193]
	s_mov_b32 m0, s44
	v_lshl_add_u64 v[228:229], s[36:37], 0, v[204:205]
	global_load_lds_dwordx4 v[230:231], off
	s_mov_b32 m0, s45
	v_lshl_add_u64 v[224:225], s[30:31], 0, v[208:209]
	global_load_lds_dwordx4 v[228:229], off
	s_mov_b32 m0, s41
	v_lshl_add_u64 v[226:227], s[30:31], 0, v[206:207]
	global_load_lds_dwordx4 v[224:225], off
	s_mov_b32 m0, s46
	s_mov_b64 s[36:37], -1
	global_load_lds_dwordx4 v[226:227], off
	s_and_b64 vcc, exec, s[34:35]
	s_cbranch_vccz .Lpk_pg_569
	s_waitcnt vmcnt(8)
	s_mov_b64 s[36:37], 0

; #define PG8_STAGE(bufoff, gbase, voff) do { _Pragma("unroll") for (int _i = 0; _i < 2; ++_i) \
;         __builtin_amdgcn_global_load_lds((const unsigned*)((const char*)(gbase) + (voff)[_i]), (PG8_LAS unsigned*)(lds + (bufoff) + ldsw + _i * 8192), 16, 0, 0); } while (0)
; #define PG8_LDA(dst, b, h) do { _Pragma("unroll") for (int m = 0; m < 4; ++m) _Pragma("unroll") for (int k = 0; k < 2; ++k) dst[m][k] = *(const PG8_LAS bf16x8*)(lds + PG8_SA(b, h) + aoff + m * 2048 + k * 1024); } while (0)
; #define PG8_LDB(dst, b, h) do { _Pragma("unroll") for (int n = 0; n < 2; ++n) _Pragma("unroll") for (int k = 0; k < 2; ++k) dst[n][k] = *(const PG8_LAS bf16x8*)(lds + PG8_SB(b, h) + boff + n * 2048 + k * 1024); } while (0)
; #define PG8_MMA(ai, bj, At, Bt) do { __builtin_amdgcn_s_setprio(1); _Pragma("unroll") for (int m = 0; m < 4; ++m) _Pragma("unroll") for (int n = 0; n < 2; ++n) _Pragma("unroll") for (int k = 0; k < 2; ++k) \
;         acc[ai][bj][m][n] = __builtin_amdgcn_mfma_f32_16x16x32_bf16(Bt[n][k], At[m][k], acc[ai][bj][m][n], 0, 0, 0); __builtin_amdgcn_s_setprio(0); } while (0)
; #define PG8_WAIT_SEL(d, w4, w8) do { if constexpr (Epi::SPLIT) { if (d) { if constexpr (Epi::NSH == 4) PG8_WAIT_V(w4); else PG8_WAIT_V(w8); } else PG8_WAIT_V(8); } else PG8_WAIT_V(8); } while (0)
; #define PG8_WAIT_L(n) asm volatile("s_waitcnt lgkmcnt(" #n ")" ::: "memory")
; #define PG8_BAR __builtin_amdgcn_s_barrier()
; #define PG8_SCHED __builtin_amdgcn_sched_barrier(0)
; template <class Epi, class Sched, bool ALIGN_EPI = false, bool SP2 = false>
; __device__ __forceinline__ void gemm_phase(PG8_LAS unsigned char* lds, const Gemm g, const Sched& S, const Epi& E) {
;     ...
;             PG8_WAIT_L(0); PG8_BAR; PG8_MMA(1, 0, At, B0); PG8_MMA(1, 1, At, B1); PG8_BAR; PG8_SCHED;
;             PG8_LDB(B0, 1, 0); PG8_LDB(B1, 1, 1); PG8_SCHED; PG8_LDA(At, 1, 0); PG8_STAGE(PG8_SA(0, 1), a2 + hstepA, voffA);
;             PG8_WAIT_SEL(defer, 12, 16); PG8_WAIT_L(0); PG8_BAR; PG8_MMA(0, 0, At, B0); PG8_MMA(0, 1, At, B1); PG8_BAR; PG8_SCHED;
.Lpk_pg_560:
	s_waitcnt lgkmcnt(0)
	s_add_i32 s59, s59, 2
	s_barrier
	s_setprio 1
	s_waitcnt lgkmcnt(0)
	v_mfma_f32_16x16x32_bf16 v[60:63], v[144:147], v[184:187], 0
	v_mfma_f32_16x16x32_bf16 v[56:59], v[152:155], v[184:187], 0
	v_mfma_f32_16x16x32_bf16 v[44:47], v[144:147], v[176:179], 0
	v_mfma_f32_16x16x32_bf16 v[40:43], v[152:155], v[176:179], 0
	v_mfma_f32_16x16x32_bf16 v[28:31], v[144:147], v[168:171], 0
	v_mfma_f32_16x16x32_bf16 v[24:27], v[152:155], v[168:171], 0
	v_mfma_f32_16x16x32_bf16 v[12:15], v[144:147], v[160:163], 0
	v_mfma_f32_16x16x32_bf16 v[8:11], v[152:155], v[160:163], 0
	v_mfma_f32_16x16x32_bf16 v[60:63], v[148:151], v[188:191], v[60:63]
	v_mfma_f32_16x16x32_bf16 v[56:59], v[156:159], v[188:191], v[56:59]
	v_mfma_f32_16x16x32_bf16 v[44:47], v[148:151], v[180:183], v[44:47]
	v_mfma_f32_16x16x32_bf16 v[40:43], v[156:159], v[180:183], v[40:43]
	v_mfma_f32_16x16x32_bf16 v[28:31], v[148:151], v[172:175], v[28:31]
	v_mfma_f32_16x16x32_bf16 v[24:27], v[156:159], v[172:175], v[24:27]
	v_mfma_f32_16x16x32_bf16 v[12:15], v[148:151], v[164:167], v[12:15]
	v_mfma_f32_16x16x32_bf16 v[8:11], v[156:159], v[164:167], v[8:11]
	s_setprio 0
	s_setprio 1
	v_mfma_f32_16x16x32_bf16 v[52:55], v[128:131], v[184:187], 0
	v_mfma_f32_16x16x32_bf16 v[48:51], v[136:139], v[184:187], 0
	v_mfma_f32_16x16x32_bf16 v[36:39], v[128:131], v[176:179], 0
	v_mfma_f32_16x16x32_bf16 v[32:35], v[136:139], v[176:179], 0
	v_mfma_f32_16x16x32_bf16 v[20:23], v[128:131], v[168:171], 0
	v_mfma_f32_16x16x32_bf16 v[16:19], v[136:139], v[168:171], 0
	v_mfma_f32_16x16x32_bf16 v[4:7], v[128:131], v[160:163], 0
	v_mfma_f32_16x16x32_bf16 v[0:3], v[136:139], v[160:163], 0
	v_mfma_f32_16x16x32_bf16 v[52:55], v[132:135], v[188:191], v[52:55]
	v_mfma_f32_16x16x32_bf16 v[48:51], v[140:143], v[188:191], v[48:51]
	v_mfma_f32_16x16x32_bf16 v[36:39], v[132:135], v[180:183], v[36:39]
	v_mfma_f32_16x16x32_bf16 v[32:35], v[140:143], v[180:183], v[32:35]
	v_mfma_f32_16x16x32_bf16 v[20:23], v[132:135], v[172:175], v[20:23]
	v_mfma_f32_16x16x32_bf16 v[16:19], v[140:143], v[172:175], v[16:19]
	v_mfma_f32_16x16x32_bf16 v[4:7], v[132:135], v[164:167], v[4:7]
	v_mfma_f32_16x16x32_bf16 v[0:3], v[140:143], v[164:167], v[0:3]
	s_setprio 0
	s_barrier
	s_add_i32 s34, 0, 0x18000
	s_add_i32 s35, 0, 0x1c000
	v_add_u32_e32 v140, s34, v239
	v_add_u32_e32 v156, s35, v239
	ds_read_b128 v[128:131], v140
	ds_read_b128 v[132:135], v140 offset:1024
	ds_read_b128 v[136:139], v140 offset:2048
	ds_read_b128 v[140:143], v140 offset:3072
	ds_read_b128 v[144:147], v156
	ds_read_b128 v[148:151], v156 offset:1024
	ds_read_b128 v[152:155], v156 offset:2048
	ds_read_b128 v[156:159], v156 offset:3072
	s_add_u32 s30, s30, s8
	s_addc_u32 s31, s31, s9
	s_mov_b32 m0, s47
	v_lshl_add_u64 v[194:195], s[30:31], 0, v[208:209]
	ds_read_b128 v[160:163], v240 offset:32768
	ds_read_b128 v[164:167], v240 offset:33792
	ds_read_b128 v[168:171], v240 offset:34816
	ds_read_b128 v[172:175], v240 offset:35840
	ds_read_b128 v[176:179], v240 offset:36864
	ds_read_b128 v[180:183], v240 offset:37888
	ds_read_b128 v[184:187], v240 offset:38912
	ds_read_b128 v[188:191], v240 offset:39936
	global_load_lds_dwordx4 v[194:195], off
	v_lshl_add_u64 v[194:195], s[30:31], 0, v[206:207]
	s_mov_b32 m0, s48
	s_nop 0
	global_load_lds_dwordx4 v[194:195], off
	s_waitcnt vmcnt(8)
	s_waitcnt lgkmcnt(0)
	s_barrier
	s_setprio 1
	s_waitcnt lgkmcnt(0)
	v_mfma_f32_16x16x32_bf16 v[124:127], v[128:131], v[160:163], v[124:127]
	v_mfma_f32_16x16x32_bf16 v[120:123], v[136:139], v[160:163], v[120:123]
	v_mfma_f32_16x16x32_bf16 v[108:111], v[128:131], v[168:171], v[108:111]
	v_mfma_f32_16x16x32_bf16 v[104:107], v[136:139], v[168:171], v[104:107]
	v_mfma_f32_16x16x32_bf16 v[92:95], v[128:131], v[176:179], v[92:95]
	v_mfma_f32_16x16x32_bf16 v[88:91], v[136:139], v[176:179], v[88:91]
	v_mfma_f32_16x16x32_bf16 v[76:79], v[128:131], v[184:187], v[76:79]
	v_mfma_f32_16x16x32_bf16 v[72:75], v[136:139], v[184:187], v[72:75]
	v_mfma_f32_16x16x32_bf16 v[124:127], v[132:135], v[164:167], v[124:127]
	v_mfma_f32_16x16x32_bf16 v[120:123], v[140:143], v[164:167], v[120:123]
	v_mfma_f32_16x16x32_bf16 v[108:111], v[132:135], v[172:175], v[108:111]
	v_mfma_f32_16x16x32_bf16 v[104:107], v[140:143], v[172:175], v[104:107]
	v_mfma_f32_16x16x32_bf16 v[92:95], v[132:135], v[180:183], v[92:95]
	v_mfma_f32_16x16x32_bf16 v[88:91], v[140:143], v[180:183], v[88:91]
	v_mfma_f32_16x16x32_bf16 v[76:79], v[132:135], v[188:191], v[76:79]
	v_mfma_f32_16x16x32_bf16 v[72:75], v[140:143], v[188:191], v[72:75]
	s_setprio 0
	s_setprio 1
	v_mfma_f32_16x16x32_bf16 v[116:119], v[144:147], v[160:163], v[116:119]
	v_mfma_f32_16x16x32_bf16 v[112:115], v[152:155], v[160:163], v[112:115]
	v_mfma_f32_16x16x32_bf16 v[100:103], v[144:147], v[168:171], v[100:103]
	v_mfma_f32_16x16x32_bf16 v[96:99], v[152:155], v[168:171], v[96:99]
	v_mfma_f32_16x16x32_bf16 v[84:87], v[144:147], v[176:179], v[84:87]
	v_mfma_f32_16x16x32_bf16 v[80:83], v[152:155], v[176:179], v[80:83]
	v_mfma_f32_16x16x32_bf16 v[68:71], v[144:147], v[184:187], v[68:71]
	v_mfma_f32_16x16x32_bf16 v[64:67], v[152:155], v[184:187], v[64:67]
	v_mfma_f32_16x16x32_bf16 v[116:119], v[148:151], v[164:167], v[116:119]
	v_mfma_f32_16x16x32_bf16 v[112:115], v[156:159], v[164:167], v[112:115]
	v_mfma_f32_16x16x32_bf16 v[100:103], v[148:151], v[172:175], v[100:103]
	v_mfma_f32_16x16x32_bf16 v[96:99], v[156:159], v[172:175], v[96:99]
	v_mfma_f32_16x16x32_bf16 v[84:87], v[148:151], v[180:183], v[84:87]
	v_mfma_f32_16x16x32_bf16 v[80:83], v[156:159], v[180:183], v[80:83]
	v_mfma_f32_16x16x32_bf16 v[68:71], v[148:151], v[188:191], v[68:71]
	v_mfma_f32_16x16x32_bf16 v[64:67], v[156:159], v[188:191], v[64:67]
	s_setprio 0
	s_barrier
; #define PG8_STAGE(bufoff, gbase, voff) do { _Pragma("unroll") for (int _i = 0; _i < 2; ++_i) \
;         __builtin_amdgcn_global_load_lds((const unsigned*)((const char*)(gbase) + (voff)[_i]), (PG8_LAS unsigned*)(lds + (bufoff) + ldsw + _i * 8192), 16, 0, 0); } while (0)
; #define PG8_LDA(dst, b, h) do { _Pragma("unroll") for (int m = 0; m < 4; ++m) _Pragma("unroll") for (int k = 0; k < 2; ++k) dst[m][k] = *(const PG8_LAS bf16x8*)(lds + PG8_SA(b, h) + aoff + m * 2048 + k * 1024); } while (0)
; #define PG8_MMA(ai, bj, At, Bt) do { __builtin_amdgcn_s_setprio(1); _Pragma("unroll") for (int m = 0; m < 4; ++m) _Pragma("unroll") for (int n = 0; n < 2; ++n) _Pragma("unroll") for (int k = 0; k < 2; ++k) \
;         acc[ai][bj][m][n] = __builtin_amdgcn_mfma_f32_16x16x32_bf16(Bt[n][k], At[m][k], acc[ai][bj][m][n], 0, 0, 0); __builtin_amdgcn_s_setprio(0); } while (0)
; #define PG8_WAIT_V(n) asm volatile("s_waitcnt vmcnt(" #n ")" ::: "memory")
; #define PG8_WAIT_L(n) asm volatile("s_waitcnt lgkmcnt(" #n ")" ::: "memory")
; #define PG8_BAR __builtin_amdgcn_s_barrier()
; #define PG8_SCHED __builtin_amdgcn_sched_barrier(0)
; template <class Epi, class Sched, bool ALIGN_EPI = false, bool SP2 = false>
; __device__ __forceinline__ void gemm_phase(PG8_LAS unsigned char* lds, const Gemm g, const Sched& S, const Epi& E) {
;     ...
;         for (int t = 0; t < nt; t += 2) {
;     ...
;             PG8_LDA(At, 1, 1); PG8_STAGE(PG8_SB(1, 0), b3, voffB); PG8_STAGE(PG8_SB(1, 1), b3 + hstep, voffB); PG8_STAGE(PG8_SA(1, 0), a3, voffA);
;             PG8_WAIT_V(8); PG8_WAIT_L(0); PG8_BAR; PG8_MMA(1, 0, At, B0); PG8_MMA(1, 1, At, B1); PG8_BAR; PG8_SCHED;
	s_add_i32 s30, s34, s40
	v_lshl_add_u64 v[194:195], v[222:223], 0, s[90:91]
	s_mov_b32 m0, s30
	ds_read_b128 v[160:163], v240 offset:49152
	ds_read_b128 v[164:167], v240 offset:50176
	ds_read_b128 v[168:171], v240 offset:51200
	ds_read_b128 v[172:175], v240 offset:52224
	ds_read_b128 v[176:179], v240 offset:53248
	ds_read_b128 v[180:183], v240 offset:54272
	ds_read_b128 v[184:187], v240 offset:55296
	ds_read_b128 v[188:191], v240 offset:56320
	global_load_lds_dwordx4 v[194:195], off
	v_lshl_add_u64 v[194:195], v[220:221], 0, s[90:91]
	s_add_i32 m0, s30, 0x2000
	s_add_i32 s30, s35, s40
	global_load_lds_dwordx4 v[194:195], off
	v_lshl_add_u64 v[194:195], v[230:231], 0, s[90:91]
	s_mov_b32 m0, s30
	s_nop 0
	global_load_lds_dwordx4 v[194:195], off
	v_lshl_add_u64 v[194:195], v[228:229], 0, s[90:91]
	s_add_i32 m0, s30, 0x2000
	s_nop 0
	global_load_lds_dwordx4 v[194:195], off
	v_lshl_add_u64 v[194:195], v[224:225], 0, s[90:91]
	s_mov_b32 m0, s53
	s_nop 0
	global_load_lds_dwordx4 v[194:195], off
	v_lshl_add_u64 v[194:195], v[226:227], 0, s[90:91]
	s_mov_b32 m0, s54
	s_nop 0
	global_load_lds_dwordx4 v[194:195], off
	s_waitcnt vmcnt(8)
	s_waitcnt lgkmcnt(0)
	s_barrier
	s_setprio 1
	s_waitcnt lgkmcnt(0)
	v_mfma_f32_16x16x32_bf16 v[60:63], v[128:131], v[160:163], v[60:63]
	v_mfma_f32_16x16x32_bf16 v[56:59], v[136:139], v[160:163], v[56:59]
	v_mfma_f32_16x16x32_bf16 v[44:47], v[128:131], v[168:171], v[44:47]
	v_mfma_f32_16x16x32_bf16 v[40:43], v[136:139], v[168:171], v[40:43]
	v_mfma_f32_16x16x32_bf16 v[28:31], v[128:131], v[176:179], v[28:31]
	v_mfma_f32_16x16x32_bf16 v[24:27], v[136:139], v[176:179], v[24:27]
	v_mfma_f32_16x16x32_bf16 v[12:15], v[128:131], v[184:187], v[12:15]
	v_mfma_f32_16x16x32_bf16 v[8:11], v[136:139], v[184:187], v[8:11]
	v_mfma_f32_16x16x32_bf16 v[60:63], v[132:135], v[164:167], v[60:63]
	v_mfma_f32_16x16x32_bf16 v[56:59], v[140:143], v[164:167], v[56:59]
	v_mfma_f32_16x16x32_bf16 v[44:47], v[132:135], v[172:175], v[44:47]
	v_mfma_f32_16x16x32_bf16 v[40:43], v[140:143], v[172:175], v[40:43]
	v_mfma_f32_16x16x32_bf16 v[28:31], v[132:135], v[180:183], v[28:31]
	v_mfma_f32_16x16x32_bf16 v[24:27], v[140:143], v[180:183], v[24:27]
	v_mfma_f32_16x16x32_bf16 v[12:15], v[132:135], v[188:191], v[12:15]
	v_mfma_f32_16x16x32_bf16 v[8:11], v[140:143], v[188:191], v[8:11]
	s_setprio 0
	s_setprio 1
	v_mfma_f32_16x16x32_bf16 v[52:55], v[144:147], v[160:163], v[52:55]
	v_mfma_f32_16x16x32_bf16 v[48:51], v[152:155], v[160:163], v[48:51]
	v_mfma_f32_16x16x32_bf16 v[36:39], v[144:147], v[168:171], v[36:39]
	v_mfma_f32_16x16x32_bf16 v[32:35], v[152:155], v[168:171], v[32:35]
	v_mfma_f32_16x16x32_bf16 v[20:23], v[144:147], v[176:179], v[20:23]
	v_mfma_f32_16x16x32_bf16 v[16:19], v[152:155], v[176:179], v[16:19]
	v_mfma_f32_16x16x32_bf16 v[4:7], v[144:147], v[184:187], v[4:7]
	v_mfma_f32_16x16x32_bf16 v[0:3], v[152:155], v[184:187], v[0:3]
	v_mfma_f32_16x16x32_bf16 v[52:55], v[148:151], v[164:167], v[52:55]
	v_mfma_f32_16x16x32_bf16 v[48:51], v[156:159], v[164:167], v[48:51]
	v_mfma_f32_16x16x32_bf16 v[36:39], v[148:151], v[172:175], v[36:39]
	v_mfma_f32_16x16x32_bf16 v[32:35], v[156:159], v[172:175], v[32:35]
	v_mfma_f32_16x16x32_bf16 v[20:23], v[148:151], v[180:183], v[20:23]
	v_mfma_f32_16x16x32_bf16 v[16:19], v[156:159], v[180:183], v[16:19]
	v_mfma_f32_16x16x32_bf16 v[4:7], v[148:151], v[188:191], v[4:7]
	v_mfma_f32_16x16x32_bf16 v[0:3], v[156:159], v[188:191], v[0:3]
	s_setprio 0
	s_barrier
	s_add_u32 s28, s28, 0x100
	s_addc_u32 s29, s29, 0
	s_add_u32 s1, s1, 0x100
	s_addc_u32 s33, s33, 0
	s_cmp_ge_i32 s59, s50
	s_cbranch_scc1 .LBB0_571
	s_branch .LBB0_561
